# 25% of the phase-1 weight-conversion work (cd_w_in, ab_w_out, cd_w_out, rg) moved to phase 0 where all workgroups convert
# speedup vs baseline: 1.0045x; 1.0016x over previous
; #define TR_JOB_GU(W_, WT_, off_, gain_) { constexpr int nnb_ = DFF / 32, nit_ = (DM / 64) * nnb_; \
;     if (r < nit_) { const int kb_ = r / nnb_, nb_ = r % nnb_, c0_ = 32 * nb_; \
;         return TrDesc{(W_) + (size_t)(64 * kb_) * DFF + c0_, (WT_) + (size_t)(256 * (c0_ / 128) + (c0_ % 128) + (off_)) * DM + 64 * kb_, (gain_) + 64 * kb_, DFF, DM}; } r -= nit_; }
; __device__ __forceinline__ TrDesc p0_item(const Params& p, int it) {
;     ...
;     TR_JOB(p.ab_w_out, DM, DM, 0, DM, WAB_OUT, 0, (const float*)nullptr)
;     TR_JOB_GU(p.ffn_w_gate, WGU0, 0, p.norm_ffn)
;     TR_JOB_GU(p.ffn_w_up, WGU0, 128, p.norm_ffn)
;     TR_JOB(p.ffn_w_down, DM, DFF, 0, DM, WDN0, 0, (const float*)nullptr)
;     TR_JOB(p.cd_w_in, CD_IN, DM, 0, CD_IN, WCD_IN, 0, p.norm_mix + DM)
;     TR_JOB_GU(p.ffn_w_gate + (size_t)DM * DFF, WGU1, 0, p.norm_ffn + DM)
;     TR_JOB_GU(p.ffn_w_up + (size_t)DM * DFF, WGU1, 128, p.norm_ffn + DM)
;     TR_JOB(p.cd_w_out, DM, DM, 0, DM, (bf16_t*)(ws + WS_WCD_OUT), 0, (const float*)nullptr)
;     const int mat = r / 32, rr = r % 32, kb_ = rr / 8, nb_ = rr % 8;
;     const float* W = (mat < 8 ? p.rg_w_x : p.rg_w_a) + (size_t)(mat & 7) * 65536;
;     return TrDesc{W + (size_t)(64 * kb_) * 256 + 32 * nb_, WRG + (size_t)mat * 65536 + (size_t)(32 * nb_) * 256 + 64 * kb_, nullptr, 256, 256};
.LBB0_66:
.Lpz_entry:
	s_mov_b64 exec, -1
	v_readlane_b32 s84, v240, 0
	v_readlane_b32 s85, v240, 1
	v_readlane_b32 s82, v240, 2
	v_readlane_b32 s83, v240, 3
	s_lshr_b32 s85, s85, 6
	s_lshl_b32 s84, s84, 3
	s_add_i32 s81, s84, s85
	s_sub_u32 s82, s82, 0xd0
	s_subb_u32 s83, s83, 0
	v_mbcnt_lo_u32_b32 v228, -1, 0
	v_mbcnt_hi_u32_b32 v228, -1, v228
	v_lshrrev_b32_e32 v238, 3, v228
	v_and_b32_e32 v239, 7, v228
	v_lshlrev_b32_e32 v237, 5, v238
.Lpz_job_cdi:
	s_load_dwordx2 s[60:61], s[82:83], 0x60
	s_load_dwordx2 s[62:63], s[82:83], 0xb8
	s_load_dwordx2 s[76:77], s[82:83], 0x8
	s_mov_b32 s78, 0xa000
	s_mov_b32 s79, 0x2000
	s_mov_b32 s75, 0
	s_and_b32 s84, s81, 63
	s_lshr_b32 s85, s81, 6
	s_add_i32 s85, s85, 0
	s_and_b32 s85, s85, 31
	s_sub_i32 s74, 79, s85
	s_lshr_b32 s74, s74, 5
	s_add_i32 s74, s74, 1
	s_lshl_b32 s86, s84, 6
	s_mul_i32 s86, s86, s78
	s_lshl_b32 s87, s85, 9
	s_add_u32 s86, s86, s87
	s_mul_i32 s88, s85, 128
	s_mul_i32 s88, s88, s79
	s_lshl_b32 s89, s84, 7
	s_add_u32 s88, s88, s89
	s_mov_b32 s70, 0x4000
	s_mov_b32 s71, 0
	s_mov_b32 s72, 0x2000000
	s_mov_b32 s73, 0
	s_waitcnt lgkmcnt(0)
	s_add_u32 s60, s60, s86
	s_addc_u32 s61, s61, 0
	s_add_u32 s62, s62, 0x18300000
	s_addc_u32 s63, s63, 0
	s_add_u32 s62, s62, s88
	s_addc_u32 s63, s63, 0
	s_lshl_b32 s89, s79, 5
	s_add_u32 s64, s62, s89
	s_addc_u32 s65, s63, 0
	s_add_u32 s66, s64, s89
	s_addc_u32 s67, s65, 0
	s_add_u32 s68, s66, s89
	s_addc_u32 s69, s67, 0
	s_add_u32 s76, s76, 0x4000
	s_addc_u32 s77, s77, 0
	s_lshl_b32 s89, s84, 8
	s_add_u32 s76, s76, s89
	s_addc_u32 s77, s77, 0
	s_mov_b32 s80, 1
	s_branch .Lpz_run
.Lpz_back_0:
.Lpz_job_abo:
	s_load_dwordx2 s[60:61], s[82:83], 0x58
	s_load_dwordx2 s[62:63], s[82:83], 0xb8
	s_mov_b32 s78, 0x4000
	s_mov_b32 s79, 0x2000
	s_mov_b32 s75, 1
	s_and_b32 s84, s81, 63
	s_lshr_b32 s85, s81, 6
	s_add_i32 s85, s85, 0
	s_and_b32 s85, s85, 31
	s_sub_i32 s74, 31, s85
	s_lshr_b32 s74, s74, 5
	s_add_i32 s74, s74, 1
	s_lshl_b32 s86, s84, 6
	s_mul_i32 s86, s86, s78
	s_lshl_b32 s87, s85, 9
	s_add_u32 s86, s86, s87
	s_mul_i32 s88, s85, 128
	s_mul_i32 s88, s88, s79
	s_lshl_b32 s89, s84, 7
	s_add_u32 s88, s88, s89
	s_mov_b32 s70, 0x4000
	s_mov_b32 s71, 0
	s_mov_b32 s72, 0x2000000
	s_mov_b32 s73, 0
	s_waitcnt lgkmcnt(0)
	s_add_u32 s60, s60, s86
	s_addc_u32 s61, s61, 0
	s_add_u32 s62, s62, 0x6100000
	s_addc_u32 s63, s63, 0
	s_add_u32 s62, s62, s88
	s_addc_u32 s63, s63, 0
	s_lshl_b32 s89, s79, 5
	s_add_u32 s64, s62, s89
	s_addc_u32 s65, s63, 0
	s_add_u32 s66, s64, s89
	s_addc_u32 s67, s65, 0
	s_add_u32 s68, s66, s89
	s_addc_u32 s69, s67, 0
	s_mov_b32 s80, 0
	s_branch .Lpz_run
.Lpz_back_1:
.Lpz_job_cdo:
	s_load_dwordx2 s[60:61], s[82:83], 0xa0
	s_load_dwordx2 s[62:63], s[82:83], 0xb8
	s_mov_b32 s78, 0x4000
	s_mov_b32 s79, 0x2000
	s_mov_b32 s75, 2
	s_and_b32 s84, s81, 63
	s_lshr_b32 s85, s81, 6
	s_add_i32 s85, s85, 16
	s_and_b32 s85, s85, 31
	s_sub_i32 s74, 31, s85
	s_lshr_b32 s74, s74, 5
	s_add_i32 s74, s74, 1
	s_lshl_b32 s86, s84, 6
	s_mul_i32 s86, s86, s78
	s_lshl_b32 s87, s85, 9
	s_add_u32 s86, s86, s87
	s_mul_i32 s88, s85, 128
	s_mul_i32 s88, s88, s79
	s_lshl_b32 s89, s84, 7
	s_add_u32 s88, s88, s89
	s_mov_b32 s70, 0x4000
	s_mov_b32 s71, 0
	s_mov_b32 s72, 0x2000000
	s_mov_b32 s73, 0
	s_waitcnt lgkmcnt(0)
	s_add_u32 s60, s60, s86
	s_addc_u32 s61, s61, 0
	s_add_u32 s62, s62, 0x1d300000
	s_addc_u32 s63, s63, 0
	s_add_u32 s62, s62, s88
	s_addc_u32 s63, s63, 0
	s_lshl_b32 s89, s79, 5
	s_add_u32 s64, s62, s89
	s_addc_u32 s65, s63, 0
	s_add_u32 s66, s64, s89
	s_addc_u32 s67, s65, 0
	s_add_u32 s68, s66, s89
	s_addc_u32 s69, s67, 0
	s_mov_b32 s80, 0
	s_branch .Lpz_run
.Lpz_back_2:
.Lpz_job_rgx:
	s_load_dwordx2 s[60:61], s[82:83], 0x78
	s_load_dwordx2 s[62:63], s[82:83], 0xb8
	s_mov_b32 s78, 0x400
	s_mov_b32 s79, 0x200
	s_mov_b32 s75, 3
	s_sub_i32 s84, s81, 1024
	s_cmp_lt_u32 s84, 64
	s_cselect_b32 s74, 1, 0
	s_and_b32 s84, s84, 63
	s_lshr_b32 s85, s84, 3
	s_bfe_u32 s87, s84, 0x20001
	s_and_b32 s89, s84, 1
	s_lshl_b32 s86, s85, 18
	s_lshl_b32 s90, s87, 16
	s_add_u32 s86, s86, s90
	s_lshl_b32 s90, s89, 9
	s_add_u32 s86, s86, s90
	s_lshl_b32 s88, s85, 17
	s_lshl_b32 s90, s89, 16
	s_add_u32 s88, s88, s90
	s_lshl_b32 s90, s87, 7
	s_add_u32 s88, s88, s90
	s_mov_b32 s70, 0
	s_mov_b32 s71, 0
	s_mov_b32 s72, 0
	s_mov_b32 s73, 0
	s_waitcnt lgkmcnt(0)
	s_add_u32 s60, s60, s86
	s_addc_u32 s61, s61, 0
	s_add_u32 s62, s62, 0x2f600000
	s_addc_u32 s63, s63, 0
	s_add_u32 s62, s62, s88
	s_addc_u32 s63, s63, 0
	s_lshl_b32 s89, s79, 5
	s_add_u32 s64, s62, s89
	s_addc_u32 s65, s63, 0
	s_add_u32 s66, s64, s89
	s_addc_u32 s67, s65, 0
	s_add_u32 s68, s66, s89
	s_addc_u32 s69, s67, 0
	s_mov_b32 s80, 0
	s_branch .Lpz_run
.Lpz_back_3:
.Lpz_job_rga:
	s_load_dwordx2 s[60:61], s[82:83], 0x88
	s_load_dwordx2 s[62:63], s[82:83], 0xb8
	s_mov_b32 s78, 0x400
	s_mov_b32 s79, 0x200
	s_mov_b32 s75, 4
	s_sub_i32 s84, s81, 1088
	s_cmp_lt_u32 s84, 64
	s_cselect_b32 s74, 1, 0
	s_and_b32 s84, s84, 63
	s_lshr_b32 s85, s84, 3
	s_bfe_u32 s87, s84, 0x20001
	s_and_b32 s89, s84, 1
	s_lshl_b32 s86, s85, 18
	s_lshl_b32 s90, s87, 16
	s_add_u32 s86, s86, s90
	s_lshl_b32 s90, s89, 9
	s_add_u32 s86, s86, s90
	s_lshl_b32 s88, s85, 17
	s_lshl_b32 s90, s89, 16
	s_add_u32 s88, s88, s90
	s_lshl_b32 s90, s87, 7
	s_add_u32 s88, s88, s90
	s_mov_b32 s70, 0
	s_mov_b32 s71, 0
	s_mov_b32 s72, 0
	s_mov_b32 s73, 0
	s_waitcnt lgkmcnt(0)
	s_add_u32 s60, s60, s86
	s_addc_u32 s61, s61, 0
	s_add_u32 s62, s62, 0x2f700000
	s_addc_u32 s63, s63, 0
	s_add_u32 s62, s62, s88
	s_addc_u32 s63, s63, 0
	s_lshl_b32 s89, s79, 5
	s_add_u32 s64, s62, s89
	s_addc_u32 s65, s63, 0
	s_add_u32 s66, s64, s89
	s_addc_u32 s67, s65, 0
	s_add_u32 s68, s66, s89
	s_addc_u32 s69, s67, 0
	s_mov_b32 s80, 0
	s_branch .Lpz_run

; template <bool NT = true> __device__ __forceinline__ void tr_load(const TrDesc& d, f32x4 (&v)[8], int lane) {
;     const float* sp = d.src + (size_t)(lane >> 3) * d.ldn + 4 * (lane & 7);
; #pragma unroll
;     for (int i = 0; i < 8; ++i) v[i] = NT ? __builtin_nontemporal_load((const f32x4*)(sp + (size_t)(8 * i) * d.ldn)) : *(const f32x4*)(sp + (size_t)(8 * i) * d.ldn);
; }
; template <bool NT = true> __device__ __forceinline__ void tr_finish(const TrDesc& d, const f32x4 (&v)[8], LAS float* scr, int lane) {
;     const int c = lane & 7;
;     f32x4 g0 = {1.f, 1.f, 1.f, 1.f}, g1 = {1.f, 1.f, 1.f, 1.f};
;     if (d.gain) { g0 = *(const f32x4*)(d.gain + 8 * c); g1 = *(const f32x4*)(d.gain + 8 * c + 4); }
; #pragma unroll
;     for (int i = 0; i < 8; ++i) { LAS float* w = scr + (8 * i + (lane >> 3)) * 33 + 4 * c; w[0] = v[i].x; w[1] = v[i].y; w[2] = v[i].z; w[3] = v[i].w; }
;     LDS_WAIT(); asm volatile("" ::: "memory");
; #pragma unroll
;     for (int j = 0; j < 4; ++j) { const int n = (lane >> 3) + 8 * j; const LAS float* s = scr + (8 * c) * 33 + n;
;         u32x4 o; o.x = cvt_pk_bf16(s[0 * 33] * g0.x, s[1 * 33] * g0.y); o.y = cvt_pk_bf16(s[2 * 33] * g0.z, s[3 * 33] * g0.w); o.z = cvt_pk_bf16(s[4 * 33] * g1.x, s[5 * 33] * g1.y); o.w = cvt_pk_bf16(s[6 * 33] * g1.z, s[7 * 33] * g1.w);
;         if (NT) __builtin_nontemporal_store(o, (u32x4*)(d.dst + (size_t)n * d.K + 8 * c)); else *(u32x4*)(d.dst + (size_t)n * d.K + 8 * c) = o; }
; template <class F, bool NT = true> __device__ __forceinline__ void tr_run(F item, int first, int step, int n, LAS float* scr, int lane) {
;     if (first >= n) return;
;     TrDesc da = item(first), db = da, dc = da; f32x4 va[8], vb[8], vc[8];
;     tr_load<NT>(da, va, lane);
;     if (first + step < n) { db = item(first + step); tr_load<NT>(db, vb, lane); }
;     for (int it = first; it < n; it += 3 * step) {
;         const bool h1 = it + step < n, h2 = it + 2 * step < n, h3 = it + 3 * step < n, h4 = it + 4 * step < n;
;         if (h2) { dc = item(it + 2 * step); tr_load<NT>(dc, vc, lane); }
;         tr_finish<NT>(da, va, scr, lane);
;         if (h3) { da = item(it + 3 * step); tr_load<NT>(da, va, lane); }
;         if (h1) tr_finish<NT>(db, vb, scr, lane);
;         if (h4) { db = item(it + 4 * step); tr_load<NT>(db, vb, lane); }
;         if (h2) tr_finish<NT>(dc, vc, scr, lane);
;     }
; }
.Lpz_run:
	s_cmp_eq_u32 s74, 0
	s_cbranch_scc1 .Lpz_ret
	v_mul_lo_u32 v229, v238, s78
	v_lshlrev_b32_e32 v229, 3, v229
	v_lshl_add_u32 v2, v239, 4, v229
	v_add_u32_e32 v120, s78, v2
	v_add_u32_e32 v121, s78, v120
	v_add_u32_e32 v126, s78, v121
	v_add_u32_e32 v144, s78, v126
	v_add_u32_e32 v145, s78, v144
	v_add_u32_e32 v147, s78, v145
	v_add_u32_e32 v165, s78, v147
	v_lshlrev_b32_e32 v230, 2, v239
	v_mul_lo_u32 v230, v230, s79
	v_lshl_add_u32 v214, v238, 4, v230
	v_add_u32_e32 v215, s79, v214
	v_add_u32_e32 v219, s79, v215
	v_add_u32_e32 v236, s79, v219
	s_cmp_eq_u32 s80, 0
	s_cbranch_scc1 .Lpz_nogain
	global_load_dwordx4 v[220:223], v237, s[76:77]
	global_load_dwordx4 v[224:227], v237, s[76:77] offset:16
	global_load_dwordx4 v[6:9], v2, s[60:61] offset:0 nt
	global_load_dwordx4 v[10:13], v120, s[60:61] offset:0 nt
	global_load_dwordx4 v[14:17], v121, s[60:61] offset:0 nt
	global_load_dwordx4 v[18:21], v126, s[60:61] offset:0 nt
	global_load_dwordx4 v[22:25], v144, s[60:61] offset:0 nt
	global_load_dwordx4 v[26:29], v145, s[60:61] offset:0 nt
	global_load_dwordx4 v[30:33], v147, s[60:61] offset:0 nt
	global_load_dwordx4 v[66:69], v165, s[60:61] offset:0 nt
	global_load_dwordx4 v[100:103], v2, s[60:61] offset:128 nt
	global_load_dwordx4 v[104:107], v120, s[60:61] offset:128 nt
	global_load_dwordx4 v[108:111], v121, s[60:61] offset:128 nt
	global_load_dwordx4 v[112:115], v126, s[60:61] offset:128 nt
	global_load_dwordx4 v[116:119], v144, s[60:61] offset:128 nt
	global_load_dwordx4 v[132:135], v145, s[60:61] offset:128 nt
	global_load_dwordx4 v[136:139], v147, s[60:61] offset:128 nt
	global_load_dwordx4 v[140:143], v165, s[60:61] offset:128 nt
	global_load_dwordx4 v[148:151], v2, s[60:61] offset:256 nt
	global_load_dwordx4 v[152:155], v120, s[60:61] offset:256 nt
	global_load_dwordx4 v[156:159], v121, s[60:61] offset:256 nt
	global_load_dwordx4 v[160:163], v126, s[60:61] offset:256 nt
	global_load_dwordx4 v[166:169], v144, s[60:61] offset:256 nt
	global_load_dwordx4 v[170:173], v145, s[60:61] offset:256 nt
	global_load_dwordx4 v[174:177], v147, s[60:61] offset:256 nt
	global_load_dwordx4 v[178:181], v165, s[60:61] offset:256 nt
	global_load_dwordx4 v[182:185], v2, s[60:61] offset:384 nt
	global_load_dwordx4 v[186:189], v120, s[60:61] offset:384 nt
	global_load_dwordx4 v[190:193], v121, s[60:61] offset:384 nt
	global_load_dwordx4 v[194:197], v126, s[60:61] offset:384 nt
	global_load_dwordx4 v[198:201], v144, s[60:61] offset:384 nt
	global_load_dwordx4 v[202:205], v145, s[60:61] offset:384 nt
	global_load_dwordx4 v[206:209], v147, s[60:61] offset:384 nt
	global_load_dwordx4 v[210:213], v165, s[60:61] offset:384 nt
	s_add_u32 s60, s60, s70
	s_addc_u32 s61, s61, s71
	s_cmp_eq_u32 s74, 1
	s_cbranch_scc1 .Lpz_g_last
	s_waitcnt vmcnt(24)
	v_mul_f32_e32 v6, v220, v6
	v_mul_f32_e32 v7, v220, v7
	v_mul_f32_e32 v8, v220, v8
	v_mul_f32_e32 v9, v220, v9
	v_mul_f32_e32 v10, v221, v10
	v_mul_f32_e32 v11, v221, v11
	v_mul_f32_e32 v12, v221, v12
	v_mul_f32_e32 v13, v221, v13
	v_mul_f32_e32 v14, v222, v14
	v_mul_f32_e32 v15, v222, v15
	v_mul_f32_e32 v16, v222, v16
	v_mul_f32_e32 v17, v222, v17
	v_mul_f32_e32 v18, v223, v18
	v_mul_f32_e32 v19, v223, v19
	v_mul_f32_e32 v20, v223, v20
	v_mul_f32_e32 v21, v223, v21
	v_mul_f32_e32 v22, v224, v22
	v_mul_f32_e32 v23, v224, v23
	v_mul_f32_e32 v24, v224, v24
	v_mul_f32_e32 v25, v224, v25
	v_mul_f32_e32 v26, v225, v26
	v_mul_f32_e32 v27, v225, v27
	v_mul_f32_e32 v28, v225, v28
	v_mul_f32_e32 v29, v225, v29
	v_mul_f32_e32 v30, v226, v30
	v_mul_f32_e32 v31, v226, v31
	v_mul_f32_e32 v32, v226, v32
	v_mul_f32_e32 v33, v226, v33
	v_mul_f32_e32 v66, v227, v66
	v_mul_f32_e32 v67, v227, v67
	v_mul_f32_e32 v68, v227, v68
	v_mul_f32_e32 v69, v227, v69
	v_cvt_pk_bf16_f32 v228, v6, v10
	v_cvt_pk_bf16_f32 v229, v14, v18
	v_cvt_pk_bf16_f32 v230, v22, v26
	v_cvt_pk_bf16_f32 v231, v30, v66
	global_store_dwordx4 v214, v[228:231], s[62:63] nt
	v_cvt_pk_bf16_f32 v232, v7, v11
	v_cvt_pk_bf16_f32 v233, v15, v19
	v_cvt_pk_bf16_f32 v234, v23, v27
	v_cvt_pk_bf16_f32 v235, v31, v67
	global_store_dwordx4 v215, v[232:235], s[62:63] nt
	v_cvt_pk_bf16_f32 v228, v8, v12
	v_cvt_pk_bf16_f32 v229, v16, v20
	v_cvt_pk_bf16_f32 v230, v24, v28
	v_cvt_pk_bf16_f32 v231, v32, v68
	global_store_dwordx4 v219, v[228:231], s[62:63] nt
	v_cvt_pk_bf16_f32 v232, v9, v13
	v_cvt_pk_bf16_f32 v233, v17, v21
	v_cvt_pk_bf16_f32 v234, v25, v29
	v_cvt_pk_bf16_f32 v235, v33, v69
	global_store_dwordx4 v236, v[232:235], s[62:63] nt
	global_load_dwordx4 v[6:9], v2, s[60:61] offset:0 nt
	global_load_dwordx4 v[10:13], v120, s[60:61] offset:0 nt
	global_load_dwordx4 v[14:17], v121, s[60:61] offset:0 nt
	global_load_dwordx4 v[18:21], v126, s[60:61] offset:0 nt
	global_load_dwordx4 v[22:25], v144, s[60:61] offset:0 nt
	global_load_dwordx4 v[26:29], v145, s[60:61] offset:0 nt
	global_load_dwordx4 v[30:33], v147, s[60:61] offset:0 nt
	global_load_dwordx4 v[66:69], v165, s[60:61] offset:0 nt
	s_add_u32 s62, s62, s72
	s_addc_u32 s63, s63, s73
	s_waitcnt vmcnt(28)
; #define LAS __attribute__((address_space(3)))
; __device__ __forceinline__ unsigned cvt_pk_bf16(float lo, float hi) { unsigned r; asm volatile("v_cvt_pk_bf16_f32 %0, %1, %2" : "=v"(r) : "v"(lo), "v"(hi)); return r; }
; #define LDS_WAIT() asm volatile("s_waitcnt lgkmcnt(0)" ::: "memory")
; __device__ __forceinline__ unsigned cvt_pk_bf16(float lo, float hi) { unsigned r; asm volatile("v_cvt_pk_bf16_f32 %0, %1, %2" : "=v"(r) : "v"(lo), "v"(hi)); return r; }
; template <bool NT = true> __device__ __forceinline__ void tr_finish(const TrDesc& d, const f32x4 (&v)[8], LAS float* scr, int lane) {
;     const int c = lane & 7;
;     f32x4 g0 = {1.f, 1.f, 1.f, 1.f}, g1 = {1.f, 1.f, 1.f, 1.f};
;     if (d.gain) { g0 = *(const f32x4*)(d.gain + 8 * c); g1 = *(const f32x4*)(d.gain + 8 * c + 4); }
; #pragma unroll
;     for (int i = 0; i < 8; ++i) { LAS float* w = scr + (8 * i + (lane >> 3)) * 33 + 4 * c; w[0] = v[i].x; w[1] = v[i].y; w[2] = v[i].z; w[3] = v[i].w; }
;     LDS_WAIT(); asm volatile("" ::: "memory");
; #pragma unroll
;     for (int j = 0; j < 4; ++j) { const int n = (lane >> 3) + 8 * j; const LAS float* s = scr + (8 * c) * 33 + n;
;         u32x4 o; o.x = cvt_pk_bf16(s[0 * 33] * g0.x, s[1 * 33] * g0.y); o.y = cvt_pk_bf16(s[2 * 33] * g0.z, s[3 * 33] * g0.w); o.z = cvt_pk_bf16(s[4 * 33] * g1.x, s[5 * 33] * g1.y); o.w = cvt_pk_bf16(s[6 * 33] * g1.z, s[7 * 33] * g1.w);
;         if (NT) __builtin_nontemporal_store(o, (u32x4*)(d.dst + (size_t)n * d.K + 8 * c)); else *(u32x4*)(d.dst + (size_t)n * d.K + 8 * c) = o; }
	v_mul_f32_e32 v100, v220, v100
	v_mul_f32_e32 v101, v220, v101
	v_mul_f32_e32 v102, v220, v102
	v_mul_f32_e32 v103, v220, v103
	v_mul_f32_e32 v104, v221, v104
	v_mul_f32_e32 v105, v221, v105
	v_mul_f32_e32 v106, v221, v106
	v_mul_f32_e32 v107, v221, v107
	v_mul_f32_e32 v108, v222, v108
	v_mul_f32_e32 v109, v222, v109
	v_mul_f32_e32 v110, v222, v110
	v_mul_f32_e32 v111, v222, v111
	v_mul_f32_e32 v112, v223, v112
	v_mul_f32_e32 v113, v223, v113
	v_mul_f32_e32 v114, v223, v114
	v_mul_f32_e32 v115, v223, v115
	v_mul_f32_e32 v116, v224, v116
	v_mul_f32_e32 v117, v224, v117
	v_mul_f32_e32 v118, v224, v118
	v_mul_f32_e32 v119, v224, v119
	v_mul_f32_e32 v132, v225, v132
	v_mul_f32_e32 v133, v225, v133
	v_mul_f32_e32 v134, v225, v134
	v_mul_f32_e32 v135, v225, v135
	v_mul_f32_e32 v136, v226, v136
	v_mul_f32_e32 v137, v226, v137
	v_mul_f32_e32 v138, v226, v138
	v_mul_f32_e32 v139, v226, v139
	v_mul_f32_e32 v140, v227, v140
	v_mul_f32_e32 v141, v227, v141
	v_mul_f32_e32 v142, v227, v142
	v_mul_f32_e32 v143, v227, v143
	v_cvt_pk_bf16_f32 v228, v100, v104
	v_cvt_pk_bf16_f32 v229, v108, v112
	v_cvt_pk_bf16_f32 v230, v116, v132
	v_cvt_pk_bf16_f32 v231, v136, v140
	global_store_dwordx4 v214, v[228:231], s[64:65] nt
	v_cvt_pk_bf16_f32 v232, v101, v105
	v_cvt_pk_bf16_f32 v233, v109, v113
	v_cvt_pk_bf16_f32 v234, v117, v133
	v_cvt_pk_bf16_f32 v235, v137, v141
	global_store_dwordx4 v215, v[232:235], s[64:65] nt
	v_cvt_pk_bf16_f32 v228, v102, v106
	v_cvt_pk_bf16_f32 v229, v110, v114
	v_cvt_pk_bf16_f32 v230, v118, v134
	v_cvt_pk_bf16_f32 v231, v138, v142
	global_store_dwordx4 v219, v[228:231], s[64:65] nt
	v_cvt_pk_bf16_f32 v232, v103, v107
	v_cvt_pk_bf16_f32 v233, v111, v115
	v_cvt_pk_bf16_f32 v234, v119, v135
	v_cvt_pk_bf16_f32 v235, v139, v143
	global_store_dwordx4 v236, v[232:235], s[64:65] nt
	global_load_dwordx4 v[100:103], v2, s[60:61] offset:128 nt
	global_load_dwordx4 v[104:107], v120, s[60:61] offset:128 nt
	global_load_dwordx4 v[108:111], v121, s[60:61] offset:128 nt
	global_load_dwordx4 v[112:115], v126, s[60:61] offset:128 nt
	global_load_dwordx4 v[116:119], v144, s[60:61] offset:128 nt
	global_load_dwordx4 v[132:135], v145, s[60:61] offset:128 nt
	global_load_dwordx4 v[136:139], v147, s[60:61] offset:128 nt
	global_load_dwordx4 v[140:143], v165, s[60:61] offset:128 nt
	s_add_u32 s64, s64, s72
	s_addc_u32 s65, s65, s73
	s_waitcnt vmcnt(32)
	v_mul_f32_e32 v148, v220, v148
	v_mul_f32_e32 v149, v220, v149
	v_mul_f32_e32 v150, v220, v150
	v_mul_f32_e32 v151, v220, v151
	v_mul_f32_e32 v152, v221, v152
	v_mul_f32_e32 v153, v221, v153
	v_mul_f32_e32 v154, v221, v154
	v_mul_f32_e32 v155, v221, v155
	v_mul_f32_e32 v156, v222, v156
	v_mul_f32_e32 v157, v222, v157
	v_mul_f32_e32 v158, v222, v158
	v_mul_f32_e32 v159, v222, v159
	v_mul_f32_e32 v160, v223, v160
	v_mul_f32_e32 v161, v223, v161
	v_mul_f32_e32 v162, v223, v162
	v_mul_f32_e32 v163, v223, v163
	v_mul_f32_e32 v166, v224, v166
	v_mul_f32_e32 v167, v224, v167
	v_mul_f32_e32 v168, v224, v168
	v_mul_f32_e32 v169, v224, v169
	v_mul_f32_e32 v170, v225, v170
	v_mul_f32_e32 v171, v225, v171
	v_mul_f32_e32 v172, v225, v172
	v_mul_f32_e32 v173, v225, v173
	v_mul_f32_e32 v174, v226, v174
	v_mul_f32_e32 v175, v226, v175
	v_mul_f32_e32 v176, v226, v176
	v_mul_f32_e32 v177, v226, v177
	v_mul_f32_e32 v178, v227, v178
	v_mul_f32_e32 v179, v227, v179
	v_mul_f32_e32 v180, v227, v180
	v_mul_f32_e32 v181, v227, v181
	v_cvt_pk_bf16_f32 v228, v148, v152
	v_cvt_pk_bf16_f32 v229, v156, v160
	v_cvt_pk_bf16_f32 v230, v166, v170
	v_cvt_pk_bf16_f32 v231, v174, v178
	global_store_dwordx4 v214, v[228:231], s[66:67] nt
	v_cvt_pk_bf16_f32 v232, v149, v153
	v_cvt_pk_bf16_f32 v233, v157, v161
	v_cvt_pk_bf16_f32 v234, v167, v171
	v_cvt_pk_bf16_f32 v235, v175, v179
	global_store_dwordx4 v215, v[232:235], s[66:67] nt
	v_cvt_pk_bf16_f32 v228, v150, v154
	v_cvt_pk_bf16_f32 v229, v158, v162
	v_cvt_pk_bf16_f32 v230, v168, v172
	v_cvt_pk_bf16_f32 v231, v176, v180
	global_store_dwordx4 v219, v[228:231], s[66:67] nt
	v_cvt_pk_bf16_f32 v232, v151, v155
	v_cvt_pk_bf16_f32 v233, v159, v163
	v_cvt_pk_bf16_f32 v234, v169, v173
	v_cvt_pk_bf16_f32 v235, v177, v181
	global_store_dwordx4 v236, v[232:235], s[66:67] nt
	global_load_dwordx4 v[148:151], v2, s[60:61] offset:256 nt
	global_load_dwordx4 v[152:155], v120, s[60:61] offset:256 nt
	global_load_dwordx4 v[156:159], v121, s[60:61] offset:256 nt
	global_load_dwordx4 v[160:163], v126, s[60:61] offset:256 nt
	global_load_dwordx4 v[166:169], v144, s[60:61] offset:256 nt
	global_load_dwordx4 v[170:173], v145, s[60:61] offset:256 nt
	global_load_dwordx4 v[174:177], v147, s[60:61] offset:256 nt
	global_load_dwordx4 v[178:181], v165, s[60:61] offset:256 nt
	s_add_u32 s66, s66, s72
	s_addc_u32 s67, s67, s73
	s_waitcnt vmcnt(36)
; #define LAS __attribute__((address_space(3)))
; __device__ __forceinline__ unsigned cvt_pk_bf16(float lo, float hi) { unsigned r; asm volatile("v_cvt_pk_bf16_f32 %0, %1, %2" : "=v"(r) : "v"(lo), "v"(hi)); return r; }
; #define LDS_WAIT() asm volatile("s_waitcnt lgkmcnt(0)" ::: "memory")
; __device__ __forceinline__ unsigned cvt_pk_bf16(float lo, float hi) { unsigned r; asm volatile("v_cvt_pk_bf16_f32 %0, %1, %2" : "=v"(r) : "v"(lo), "v"(hi)); return r; }
; template <bool NT = true> __device__ __forceinline__ void tr_finish(const TrDesc& d, const f32x4 (&v)[8], LAS float* scr, int lane) {
;     const int c = lane & 7;
;     f32x4 g0 = {1.f, 1.f, 1.f, 1.f}, g1 = {1.f, 1.f, 1.f, 1.f};
;     if (d.gain) { g0 = *(const f32x4*)(d.gain + 8 * c); g1 = *(const f32x4*)(d.gain + 8 * c + 4); }
; #pragma unroll
;     for (int i = 0; i < 8; ++i) { LAS float* w = scr + (8 * i + (lane >> 3)) * 33 + 4 * c; w[0] = v[i].x; w[1] = v[i].y; w[2] = v[i].z; w[3] = v[i].w; }
;     LDS_WAIT(); asm volatile("" ::: "memory");
; #pragma unroll
;     for (int j = 0; j < 4; ++j) { const int n = (lane >> 3) + 8 * j; const LAS float* s = scr + (8 * c) * 33 + n;
;         u32x4 o; o.x = cvt_pk_bf16(s[0 * 33] * g0.x, s[1 * 33] * g0.y); o.y = cvt_pk_bf16(s[2 * 33] * g0.z, s[3 * 33] * g0.w); o.z = cvt_pk_bf16(s[4 * 33] * g1.x, s[5 * 33] * g1.y); o.w = cvt_pk_bf16(s[6 * 33] * g1.z, s[7 * 33] * g1.w);
;         if (NT) __builtin_nontemporal_store(o, (u32x4*)(d.dst + (size_t)n * d.K + 8 * c)); else *(u32x4*)(d.dst + (size_t)n * d.K + 8 * c) = o; }
; template <class F, bool NT = true> __device__ __forceinline__ void tr_run(F item, int first, int step, int n, LAS float* scr, int lane) {
;     ...
;     for (int it = first; it < n; it += 3 * step) {
;         const bool h1 = it + step < n, h2 = it + 2 * step < n, h3 = it + 3 * step < n, h4 = it + 4 * step < n;
;         if (h2) { dc = item(it + 2 * step); tr_load<NT>(dc, vc, lane); }
;         tr_finish<NT>(da, va, scr, lane);
;         if (h3) { da = item(it + 3 * step); tr_load<NT>(da, va, lane); }
;         if (h1) tr_finish<NT>(db, vb, scr, lane);
;         if (h4) { db = item(it + 4 * step); tr_load<NT>(db, vb, lane); }
;         if (h2) tr_finish<NT>(dc, vc, scr, lane);
;     }
	v_mul_f32_e32 v182, v220, v182
	v_mul_f32_e32 v183, v220, v183
	v_mul_f32_e32 v184, v220, v184
	v_mul_f32_e32 v185, v220, v185
	v_mul_f32_e32 v186, v221, v186
	v_mul_f32_e32 v187, v221, v187
	v_mul_f32_e32 v188, v221, v188
	v_mul_f32_e32 v189, v221, v189
	v_mul_f32_e32 v190, v222, v190
	v_mul_f32_e32 v191, v222, v191
	v_mul_f32_e32 v192, v222, v192
	v_mul_f32_e32 v193, v222, v193
	v_mul_f32_e32 v194, v223, v194
	v_mul_f32_e32 v195, v223, v195
	v_mul_f32_e32 v196, v223, v196
	v_mul_f32_e32 v197, v223, v197
	v_mul_f32_e32 v198, v224, v198
	v_mul_f32_e32 v199, v224, v199
	v_mul_f32_e32 v200, v224, v200
	v_mul_f32_e32 v201, v224, v201
	v_mul_f32_e32 v202, v225, v202
	v_mul_f32_e32 v203, v225, v203
	v_mul_f32_e32 v204, v225, v204
	v_mul_f32_e32 v205, v225, v205
	v_mul_f32_e32 v206, v226, v206
	v_mul_f32_e32 v207, v226, v207
	v_mul_f32_e32 v208, v226, v208
	v_mul_f32_e32 v209, v226, v209
	v_mul_f32_e32 v210, v227, v210
	v_mul_f32_e32 v211, v227, v211
	v_mul_f32_e32 v212, v227, v212
	v_mul_f32_e32 v213, v227, v213
	v_cvt_pk_bf16_f32 v228, v182, v186
	v_cvt_pk_bf16_f32 v229, v190, v194
	v_cvt_pk_bf16_f32 v230, v198, v202
	v_cvt_pk_bf16_f32 v231, v206, v210
	global_store_dwordx4 v214, v[228:231], s[68:69] nt
	v_cvt_pk_bf16_f32 v232, v183, v187
	v_cvt_pk_bf16_f32 v233, v191, v195
	v_cvt_pk_bf16_f32 v234, v199, v203
	v_cvt_pk_bf16_f32 v235, v207, v211
	global_store_dwordx4 v215, v[232:235], s[68:69] nt
	v_cvt_pk_bf16_f32 v228, v184, v188
	v_cvt_pk_bf16_f32 v229, v192, v196
	v_cvt_pk_bf16_f32 v230, v200, v204
	v_cvt_pk_bf16_f32 v231, v208, v212
	global_store_dwordx4 v219, v[228:231], s[68:69] nt
	v_cvt_pk_bf16_f32 v232, v185, v189
	v_cvt_pk_bf16_f32 v233, v193, v197
	v_cvt_pk_bf16_f32 v234, v201, v205
	v_cvt_pk_bf16_f32 v235, v209, v213
	global_store_dwordx4 v236, v[232:235], s[68:69] nt
	global_load_dwordx4 v[182:185], v2, s[60:61] offset:384 nt
	global_load_dwordx4 v[186:189], v120, s[60:61] offset:384 nt
	global_load_dwordx4 v[190:193], v121, s[60:61] offset:384 nt
	global_load_dwordx4 v[194:197], v126, s[60:61] offset:384 nt
	global_load_dwordx4 v[198:201], v144, s[60:61] offset:384 nt
	global_load_dwordx4 v[202:205], v145, s[60:61] offset:384 nt
	global_load_dwordx4 v[206:209], v147, s[60:61] offset:384 nt
	global_load_dwordx4 v[210:213], v165, s[60:61] offset:384 nt
	s_add_u32 s68, s68, s72
	s_addc_u32 s69, s69, s73
	s_add_u32 s60, s60, s70
	s_addc_u32 s61, s61, s71
	s_sub_i32 s74, s74, 1
	s_cmp_eq_u32 s74, 1
	s_cbranch_scc1 .Lpz_g_last
.Lpz_g_steady:
	s_waitcnt vmcnt(36)
	v_mul_f32_e32 v6, v220, v6
	v_mul_f32_e32 v7, v220, v7
	v_mul_f32_e32 v8, v220, v8
	v_mul_f32_e32 v9, v220, v9
	v_mul_f32_e32 v10, v221, v10
	v_mul_f32_e32 v11, v221, v11
	v_mul_f32_e32 v12, v221, v12
	v_mul_f32_e32 v13, v221, v13
	v_mul_f32_e32 v14, v222, v14
	v_mul_f32_e32 v15, v222, v15
	v_mul_f32_e32 v16, v222, v16
	v_mul_f32_e32 v17, v222, v17
	v_mul_f32_e32 v18, v223, v18
	v_mul_f32_e32 v19, v223, v19
	v_mul_f32_e32 v20, v223, v20
	v_mul_f32_e32 v21, v223, v21
	v_mul_f32_e32 v22, v224, v22
	v_mul_f32_e32 v23, v224, v23
	v_mul_f32_e32 v24, v224, v24
	v_mul_f32_e32 v25, v224, v25
	v_mul_f32_e32 v26, v225, v26
	v_mul_f32_e32 v27, v225, v27
	v_mul_f32_e32 v28, v225, v28
	v_mul_f32_e32 v29, v225, v29
	v_mul_f32_e32 v30, v226, v30
	v_mul_f32_e32 v31, v226, v31
	v_mul_f32_e32 v32, v226, v32
	v_mul_f32_e32 v33, v226, v33
	v_mul_f32_e32 v66, v227, v66
	v_mul_f32_e32 v67, v227, v67
	v_mul_f32_e32 v68, v227, v68
	v_mul_f32_e32 v69, v227, v69
	v_cvt_pk_bf16_f32 v228, v6, v10
	v_cvt_pk_bf16_f32 v229, v14, v18
	v_cvt_pk_bf16_f32 v230, v22, v26
	v_cvt_pk_bf16_f32 v231, v30, v66
	global_store_dwordx4 v214, v[228:231], s[62:63] nt
	v_cvt_pk_bf16_f32 v232, v7, v11
	v_cvt_pk_bf16_f32 v233, v15, v19
	v_cvt_pk_bf16_f32 v234, v23, v27
	v_cvt_pk_bf16_f32 v235, v31, v67
	global_store_dwordx4 v215, v[232:235], s[62:63] nt
	v_cvt_pk_bf16_f32 v228, v8, v12
	v_cvt_pk_bf16_f32 v229, v16, v20
	v_cvt_pk_bf16_f32 v230, v24, v28
	v_cvt_pk_bf16_f32 v231, v32, v68
	global_store_dwordx4 v219, v[228:231], s[62:63] nt
	v_cvt_pk_bf16_f32 v232, v9, v13
	v_cvt_pk_bf16_f32 v233, v17, v21
	v_cvt_pk_bf16_f32 v234, v25, v29
	v_cvt_pk_bf16_f32 v235, v33, v69
	global_store_dwordx4 v236, v[232:235], s[62:63] nt
	global_load_dwordx4 v[6:9], v2, s[60:61] offset:0 nt
	global_load_dwordx4 v[10:13], v120, s[60:61] offset:0 nt
	global_load_dwordx4 v[14:17], v121, s[60:61] offset:0 nt
	global_load_dwordx4 v[18:21], v126, s[60:61] offset:0 nt
	global_load_dwordx4 v[22:25], v144, s[60:61] offset:0 nt
	global_load_dwordx4 v[26:29], v145, s[60:61] offset:0 nt
	global_load_dwordx4 v[30:33], v147, s[60:61] offset:0 nt
	global_load_dwordx4 v[66:69], v165, s[60:61] offset:0 nt
	s_add_u32 s62, s62, s72
	s_addc_u32 s63, s63, s73
	s_waitcnt vmcnt(36)
; #define LAS __attribute__((address_space(3)))
; __device__ __forceinline__ unsigned cvt_pk_bf16(float lo, float hi) { unsigned r; asm volatile("v_cvt_pk_bf16_f32 %0, %1, %2" : "=v"(r) : "v"(lo), "v"(hi)); return r; }
; #define LDS_WAIT() asm volatile("s_waitcnt lgkmcnt(0)" ::: "memory")
; __device__ __forceinline__ unsigned cvt_pk_bf16(float lo, float hi) { unsigned r; asm volatile("v_cvt_pk_bf16_f32 %0, %1, %2" : "=v"(r) : "v"(lo), "v"(hi)); return r; }
; template <bool NT = true> __device__ __forceinline__ void tr_finish(const TrDesc& d, const f32x4 (&v)[8], LAS float* scr, int lane) {
;     const int c = lane & 7;
;     f32x4 g0 = {1.f, 1.f, 1.f, 1.f}, g1 = {1.f, 1.f, 1.f, 1.f};
;     if (d.gain) { g0 = *(const f32x4*)(d.gain + 8 * c); g1 = *(const f32x4*)(d.gain + 8 * c + 4); }
; #pragma unroll
;     for (int i = 0; i < 8; ++i) { LAS float* w = scr + (8 * i + (lane >> 3)) * 33 + 4 * c; w[0] = v[i].x; w[1] = v[i].y; w[2] = v[i].z; w[3] = v[i].w; }
;     LDS_WAIT(); asm volatile("" ::: "memory");
; #pragma unroll
;     for (int j = 0; j < 4; ++j) { const int n = (lane >> 3) + 8 * j; const LAS float* s = scr + (8 * c) * 33 + n;
;         u32x4 o; o.x = cvt_pk_bf16(s[0 * 33] * g0.x, s[1 * 33] * g0.y); o.y = cvt_pk_bf16(s[2 * 33] * g0.z, s[3 * 33] * g0.w); o.z = cvt_pk_bf16(s[4 * 33] * g1.x, s[5 * 33] * g1.y); o.w = cvt_pk_bf16(s[6 * 33] * g1.z, s[7 * 33] * g1.w);
;         if (NT) __builtin_nontemporal_store(o, (u32x4*)(d.dst + (size_t)n * d.K + 8 * c)); else *(u32x4*)(d.dst + (size_t)n * d.K + 8 * c) = o; }
	v_mul_f32_e32 v100, v220, v100
	v_mul_f32_e32 v101, v220, v101
	v_mul_f32_e32 v102, v220, v102
	v_mul_f32_e32 v103, v220, v103
	v_mul_f32_e32 v104, v221, v104
	v_mul_f32_e32 v105, v221, v105
	v_mul_f32_e32 v106, v221, v106
	v_mul_f32_e32 v107, v221, v107
	v_mul_f32_e32 v108, v222, v108
	v_mul_f32_e32 v109, v222, v109
	v_mul_f32_e32 v110, v222, v110
	v_mul_f32_e32 v111, v222, v111
	v_mul_f32_e32 v112, v223, v112
	v_mul_f32_e32 v113, v223, v113
	v_mul_f32_e32 v114, v223, v114
	v_mul_f32_e32 v115, v223, v115
	v_mul_f32_e32 v116, v224, v116
	v_mul_f32_e32 v117, v224, v117
	v_mul_f32_e32 v118, v224, v118
	v_mul_f32_e32 v119, v224, v119
	v_mul_f32_e32 v132, v225, v132
	v_mul_f32_e32 v133, v225, v133
	v_mul_f32_e32 v134, v225, v134
	v_mul_f32_e32 v135, v225, v135
	v_mul_f32_e32 v136, v226, v136
	v_mul_f32_e32 v137, v226, v137
	v_mul_f32_e32 v138, v226, v138
	v_mul_f32_e32 v139, v226, v139
	v_mul_f32_e32 v140, v227, v140
	v_mul_f32_e32 v141, v227, v141
	v_mul_f32_e32 v142, v227, v142
	v_mul_f32_e32 v143, v227, v143
	v_cvt_pk_bf16_f32 v228, v100, v104
	v_cvt_pk_bf16_f32 v229, v108, v112
	v_cvt_pk_bf16_f32 v230, v116, v132
	v_cvt_pk_bf16_f32 v231, v136, v140
	global_store_dwordx4 v214, v[228:231], s[64:65] nt
	v_cvt_pk_bf16_f32 v232, v101, v105
	v_cvt_pk_bf16_f32 v233, v109, v113
	v_cvt_pk_bf16_f32 v234, v117, v133
	v_cvt_pk_bf16_f32 v235, v137, v141
	global_store_dwordx4 v215, v[232:235], s[64:65] nt
	v_cvt_pk_bf16_f32 v228, v102, v106
	v_cvt_pk_bf16_f32 v229, v110, v114
	v_cvt_pk_bf16_f32 v230, v118, v134
	v_cvt_pk_bf16_f32 v231, v138, v142
	global_store_dwordx4 v219, v[228:231], s[64:65] nt
	v_cvt_pk_bf16_f32 v232, v103, v107
	v_cvt_pk_bf16_f32 v233, v111, v115
	v_cvt_pk_bf16_f32 v234, v119, v135
	v_cvt_pk_bf16_f32 v235, v139, v143
	global_store_dwordx4 v236, v[232:235], s[64:65] nt
	global_load_dwordx4 v[100:103], v2, s[60:61] offset:128 nt
	global_load_dwordx4 v[104:107], v120, s[60:61] offset:128 nt
	global_load_dwordx4 v[108:111], v121, s[60:61] offset:128 nt
	global_load_dwordx4 v[112:115], v126, s[60:61] offset:128 nt
	global_load_dwordx4 v[116:119], v144, s[60:61] offset:128 nt
	global_load_dwordx4 v[132:135], v145, s[60:61] offset:128 nt
	global_load_dwordx4 v[136:139], v147, s[60:61] offset:128 nt
	global_load_dwordx4 v[140:143], v165, s[60:61] offset:128 nt
	s_add_u32 s64, s64, s72
	s_addc_u32 s65, s65, s73
	s_waitcnt vmcnt(36)
	v_mul_f32_e32 v148, v220, v148
	v_mul_f32_e32 v149, v220, v149
	v_mul_f32_e32 v150, v220, v150
	v_mul_f32_e32 v151, v220, v151
	v_mul_f32_e32 v152, v221, v152
	v_mul_f32_e32 v153, v221, v153
	v_mul_f32_e32 v154, v221, v154
	v_mul_f32_e32 v155, v221, v155
	v_mul_f32_e32 v156, v222, v156
	v_mul_f32_e32 v157, v222, v157
	v_mul_f32_e32 v158, v222, v158
	v_mul_f32_e32 v159, v222, v159
	v_mul_f32_e32 v160, v223, v160
	v_mul_f32_e32 v161, v223, v161
	v_mul_f32_e32 v162, v223, v162
	v_mul_f32_e32 v163, v223, v163
	v_mul_f32_e32 v166, v224, v166
	v_mul_f32_e32 v167, v224, v167
	v_mul_f32_e32 v168, v224, v168
	v_mul_f32_e32 v169, v224, v169
	v_mul_f32_e32 v170, v225, v170
	v_mul_f32_e32 v171, v225, v171
	v_mul_f32_e32 v172, v225, v172
	v_mul_f32_e32 v173, v225, v173
	v_mul_f32_e32 v174, v226, v174
	v_mul_f32_e32 v175, v226, v175
	v_mul_f32_e32 v176, v226, v176
	v_mul_f32_e32 v177, v226, v177
	v_mul_f32_e32 v178, v227, v178
	v_mul_f32_e32 v179, v227, v179
	v_mul_f32_e32 v180, v227, v180
	v_mul_f32_e32 v181, v227, v181
	v_cvt_pk_bf16_f32 v228, v148, v152
	v_cvt_pk_bf16_f32 v229, v156, v160
	v_cvt_pk_bf16_f32 v230, v166, v170
	v_cvt_pk_bf16_f32 v231, v174, v178
	global_store_dwordx4 v214, v[228:231], s[66:67] nt
	v_cvt_pk_bf16_f32 v232, v149, v153
	v_cvt_pk_bf16_f32 v233, v157, v161
	v_cvt_pk_bf16_f32 v234, v167, v171
	v_cvt_pk_bf16_f32 v235, v175, v179
	global_store_dwordx4 v215, v[232:235], s[66:67] nt
	v_cvt_pk_bf16_f32 v228, v150, v154
	v_cvt_pk_bf16_f32 v229, v158, v162
	v_cvt_pk_bf16_f32 v230, v168, v172
	v_cvt_pk_bf16_f32 v231, v176, v180
	global_store_dwordx4 v219, v[228:231], s[66:67] nt
	v_cvt_pk_bf16_f32 v232, v151, v155
	v_cvt_pk_bf16_f32 v233, v159, v163
	v_cvt_pk_bf16_f32 v234, v169, v173
	v_cvt_pk_bf16_f32 v235, v177, v181
	global_store_dwordx4 v236, v[232:235], s[66:67] nt
	global_load_dwordx4 v[148:151], v2, s[60:61] offset:256 nt
	global_load_dwordx4 v[152:155], v120, s[60:61] offset:256 nt
	global_load_dwordx4 v[156:159], v121, s[60:61] offset:256 nt
	global_load_dwordx4 v[160:163], v126, s[60:61] offset:256 nt
	global_load_dwordx4 v[166:169], v144, s[60:61] offset:256 nt
	global_load_dwordx4 v[170:173], v145, s[60:61] offset:256 nt
	global_load_dwordx4 v[174:177], v147, s[60:61] offset:256 nt
	global_load_dwordx4 v[178:181], v165, s[60:61] offset:256 nt
	s_add_u32 s66, s66, s72
	s_addc_u32 s67, s67, s73
	s_waitcnt vmcnt(36)
; #define LAS __attribute__((address_space(3)))
; __device__ __forceinline__ unsigned cvt_pk_bf16(float lo, float hi) { unsigned r; asm volatile("v_cvt_pk_bf16_f32 %0, %1, %2" : "=v"(r) : "v"(lo), "v"(hi)); return r; }
; #define LDS_WAIT() asm volatile("s_waitcnt lgkmcnt(0)" ::: "memory")
; __device__ __forceinline__ unsigned cvt_pk_bf16(float lo, float hi) { unsigned r; asm volatile("v_cvt_pk_bf16_f32 %0, %1, %2" : "=v"(r) : "v"(lo), "v"(hi)); return r; }
; template <bool NT = true> __device__ __forceinline__ void tr_finish(const TrDesc& d, const f32x4 (&v)[8], LAS float* scr, int lane) {
;     const int c = lane & 7;
;     f32x4 g0 = {1.f, 1.f, 1.f, 1.f}, g1 = {1.f, 1.f, 1.f, 1.f};
;     if (d.gain) { g0 = *(const f32x4*)(d.gain + 8 * c); g1 = *(const f32x4*)(d.gain + 8 * c + 4); }
; #pragma unroll
;     for (int i = 0; i < 8; ++i) { LAS float* w = scr + (8 * i + (lane >> 3)) * 33 + 4 * c; w[0] = v[i].x; w[1] = v[i].y; w[2] = v[i].z; w[3] = v[i].w; }
;     LDS_WAIT(); asm volatile("" ::: "memory");
; #pragma unroll
;     for (int j = 0; j < 4; ++j) { const int n = (lane >> 3) + 8 * j; const LAS float* s = scr + (8 * c) * 33 + n;
;         u32x4 o; o.x = cvt_pk_bf16(s[0 * 33] * g0.x, s[1 * 33] * g0.y); o.y = cvt_pk_bf16(s[2 * 33] * g0.z, s[3 * 33] * g0.w); o.z = cvt_pk_bf16(s[4 * 33] * g1.x, s[5 * 33] * g1.y); o.w = cvt_pk_bf16(s[6 * 33] * g1.z, s[7 * 33] * g1.w);
;         if (NT) __builtin_nontemporal_store(o, (u32x4*)(d.dst + (size_t)n * d.K + 8 * c)); else *(u32x4*)(d.dst + (size_t)n * d.K + 8 * c) = o; }
; template <class F, bool NT = true> __device__ __forceinline__ void tr_run(F item, int first, int step, int n, LAS float* scr, int lane) {
;     ...
;     for (int it = first; it < n; it += 3 * step) {
;         const bool h1 = it + step < n, h2 = it + 2 * step < n, h3 = it + 3 * step < n, h4 = it + 4 * step < n;
;         if (h2) { dc = item(it + 2 * step); tr_load<NT>(dc, vc, lane); }
;         tr_finish<NT>(da, va, scr, lane);
;         if (h3) { da = item(it + 3 * step); tr_load<NT>(da, va, lane); }
;         if (h1) tr_finish<NT>(db, vb, scr, lane);
;         if (h4) { db = item(it + 4 * step); tr_load<NT>(db, vb, lane); }
;         if (h2) tr_finish<NT>(dc, vc, scr, lane);
;     }
	v_mul_f32_e32 v182, v220, v182
	v_mul_f32_e32 v183, v220, v183
	v_mul_f32_e32 v184, v220, v184
	v_mul_f32_e32 v185, v220, v185
	v_mul_f32_e32 v186, v221, v186
	v_mul_f32_e32 v187, v221, v187
	v_mul_f32_e32 v188, v221, v188
	v_mul_f32_e32 v189, v221, v189
	v_mul_f32_e32 v190, v222, v190
	v_mul_f32_e32 v191, v222, v191
	v_mul_f32_e32 v192, v222, v192
	v_mul_f32_e32 v193, v222, v193
	v_mul_f32_e32 v194, v223, v194
	v_mul_f32_e32 v195, v223, v195
	v_mul_f32_e32 v196, v223, v196
	v_mul_f32_e32 v197, v223, v197
	v_mul_f32_e32 v198, v224, v198
	v_mul_f32_e32 v199, v224, v199
	v_mul_f32_e32 v200, v224, v200
	v_mul_f32_e32 v201, v224, v201
	v_mul_f32_e32 v202, v225, v202
	v_mul_f32_e32 v203, v225, v203
	v_mul_f32_e32 v204, v225, v204
	v_mul_f32_e32 v205, v225, v205
	v_mul_f32_e32 v206, v226, v206
	v_mul_f32_e32 v207, v226, v207
	v_mul_f32_e32 v208, v226, v208
	v_mul_f32_e32 v209, v226, v209
	v_mul_f32_e32 v210, v227, v210
	v_mul_f32_e32 v211, v227, v211
	v_mul_f32_e32 v212, v227, v212
	v_mul_f32_e32 v213, v227, v213
	v_cvt_pk_bf16_f32 v228, v182, v186
	v_cvt_pk_bf16_f32 v229, v190, v194
	v_cvt_pk_bf16_f32 v230, v198, v202
	v_cvt_pk_bf16_f32 v231, v206, v210
	global_store_dwordx4 v214, v[228:231], s[68:69] nt
	v_cvt_pk_bf16_f32 v232, v183, v187
	v_cvt_pk_bf16_f32 v233, v191, v195
	v_cvt_pk_bf16_f32 v234, v199, v203
	v_cvt_pk_bf16_f32 v235, v207, v211
	global_store_dwordx4 v215, v[232:235], s[68:69] nt
	v_cvt_pk_bf16_f32 v228, v184, v188
	v_cvt_pk_bf16_f32 v229, v192, v196
	v_cvt_pk_bf16_f32 v230, v200, v204
	v_cvt_pk_bf16_f32 v231, v208, v212
	global_store_dwordx4 v219, v[228:231], s[68:69] nt
	v_cvt_pk_bf16_f32 v232, v185, v189
	v_cvt_pk_bf16_f32 v233, v193, v197
	v_cvt_pk_bf16_f32 v234, v201, v205
	v_cvt_pk_bf16_f32 v235, v209, v213
	global_store_dwordx4 v236, v[232:235], s[68:69] nt
	global_load_dwordx4 v[182:185], v2, s[60:61] offset:384 nt
	global_load_dwordx4 v[186:189], v120, s[60:61] offset:384 nt
	global_load_dwordx4 v[190:193], v121, s[60:61] offset:384 nt
	global_load_dwordx4 v[194:197], v126, s[60:61] offset:384 nt
	global_load_dwordx4 v[198:201], v144, s[60:61] offset:384 nt
	global_load_dwordx4 v[202:205], v145, s[60:61] offset:384 nt
	global_load_dwordx4 v[206:209], v147, s[60:61] offset:384 nt
	global_load_dwordx4 v[210:213], v165, s[60:61] offset:384 nt
	s_add_u32 s68, s68, s72
	s_addc_u32 s69, s69, s73
	s_add_u32 s60, s60, s70
	s_addc_u32 s61, s61, s71
	s_sub_i32 s74, s74, 1
	s_cmp_eq_u32 s74, 1
	s_cbranch_scc0 .Lpz_g_steady
.Lpz_g_last:
	s_waitcnt vmcnt(24)
	v_mul_f32_e32 v6, v220, v6
	v_mul_f32_e32 v7, v220, v7
	v_mul_f32_e32 v8, v220, v8
	v_mul_f32_e32 v9, v220, v9
	v_mul_f32_e32 v10, v221, v10
	v_mul_f32_e32 v11, v221, v11
	v_mul_f32_e32 v12, v221, v12
	v_mul_f32_e32 v13, v221, v13
	v_mul_f32_e32 v14, v222, v14
	v_mul_f32_e32 v15, v222, v15
	v_mul_f32_e32 v16, v222, v16
	v_mul_f32_e32 v17, v222, v17
	v_mul_f32_e32 v18, v223, v18
	v_mul_f32_e32 v19, v223, v19
	v_mul_f32_e32 v20, v223, v20
	v_mul_f32_e32 v21, v223, v21
	v_mul_f32_e32 v22, v224, v22
	v_mul_f32_e32 v23, v224, v23
	v_mul_f32_e32 v24, v224, v24
	v_mul_f32_e32 v25, v224, v25
	v_mul_f32_e32 v26, v225, v26
	v_mul_f32_e32 v27, v225, v27
	v_mul_f32_e32 v28, v225, v28
	v_mul_f32_e32 v29, v225, v29
	v_mul_f32_e32 v30, v226, v30
	v_mul_f32_e32 v31, v226, v31
	v_mul_f32_e32 v32, v226, v32
	v_mul_f32_e32 v33, v226, v33
	v_mul_f32_e32 v66, v227, v66
	v_mul_f32_e32 v67, v227, v67
	v_mul_f32_e32 v68, v227, v68
	v_mul_f32_e32 v69, v227, v69
	v_cvt_pk_bf16_f32 v228, v6, v10
	v_cvt_pk_bf16_f32 v229, v14, v18
	v_cvt_pk_bf16_f32 v230, v22, v26
	v_cvt_pk_bf16_f32 v231, v30, v66
	global_store_dwordx4 v214, v[228:231], s[62:63] nt
	v_cvt_pk_bf16_f32 v232, v7, v11
	v_cvt_pk_bf16_f32 v233, v15, v19
	v_cvt_pk_bf16_f32 v234, v23, v27
	v_cvt_pk_bf16_f32 v235, v31, v67
	global_store_dwordx4 v215, v[232:235], s[62:63] nt
	v_cvt_pk_bf16_f32 v228, v8, v12
	v_cvt_pk_bf16_f32 v229, v16, v20
	v_cvt_pk_bf16_f32 v230, v24, v28
	v_cvt_pk_bf16_f32 v231, v32, v68
	global_store_dwordx4 v219, v[228:231], s[62:63] nt
	v_cvt_pk_bf16_f32 v232, v9, v13
	v_cvt_pk_bf16_f32 v233, v17, v21
	v_cvt_pk_bf16_f32 v234, v25, v29
	v_cvt_pk_bf16_f32 v235, v33, v69
	global_store_dwordx4 v236, v[232:235], s[62:63] nt
	s_waitcnt vmcnt(20)
	v_mul_f32_e32 v100, v220, v100
	v_mul_f32_e32 v101, v220, v101
	v_mul_f32_e32 v102, v220, v102
	v_mul_f32_e32 v103, v220, v103
	v_mul_f32_e32 v104, v221, v104
	v_mul_f32_e32 v105, v221, v105
	v_mul_f32_e32 v106, v221, v106
	v_mul_f32_e32 v107, v221, v107
	v_mul_f32_e32 v108, v222, v108
	v_mul_f32_e32 v109, v222, v109
	v_mul_f32_e32 v110, v222, v110
	v_mul_f32_e32 v111, v222, v111
	v_mul_f32_e32 v112, v223, v112
	v_mul_f32_e32 v113, v223, v113
	v_mul_f32_e32 v114, v223, v114
	v_mul_f32_e32 v115, v223, v115
	v_mul_f32_e32 v116, v224, v116
	v_mul_f32_e32 v117, v224, v117
	v_mul_f32_e32 v118, v224, v118
	v_mul_f32_e32 v119, v224, v119
	v_mul_f32_e32 v132, v225, v132
	v_mul_f32_e32 v133, v225, v133
	v_mul_f32_e32 v134, v225, v134
	v_mul_f32_e32 v135, v225, v135
	v_mul_f32_e32 v136, v226, v136
	v_mul_f32_e32 v137, v226, v137
	v_mul_f32_e32 v138, v226, v138
	v_mul_f32_e32 v139, v226, v139
	v_mul_f32_e32 v140, v227, v140
	v_mul_f32_e32 v141, v227, v141
	v_mul_f32_e32 v142, v227, v142
	v_mul_f32_e32 v143, v227, v143
	v_cvt_pk_bf16_f32 v228, v100, v104
	v_cvt_pk_bf16_f32 v229, v108, v112
	v_cvt_pk_bf16_f32 v230, v116, v132
	v_cvt_pk_bf16_f32 v231, v136, v140
	global_store_dwordx4 v214, v[228:231], s[64:65] nt
	v_cvt_pk_bf16_f32 v232, v101, v105
	v_cvt_pk_bf16_f32 v233, v109, v113
	v_cvt_pk_bf16_f32 v234, v117, v133
	v_cvt_pk_bf16_f32 v235, v137, v141
	global_store_dwordx4 v215, v[232:235], s[64:65] nt
	v_cvt_pk_bf16_f32 v228, v102, v106
	v_cvt_pk_bf16_f32 v229, v110, v114
	v_cvt_pk_bf16_f32 v230, v118, v134
	v_cvt_pk_bf16_f32 v231, v138, v142
	global_store_dwordx4 v219, v[228:231], s[64:65] nt
	v_cvt_pk_bf16_f32 v232, v103, v107
	v_cvt_pk_bf16_f32 v233, v111, v115
	v_cvt_pk_bf16_f32 v234, v119, v135
	v_cvt_pk_bf16_f32 v235, v139, v143
	global_store_dwordx4 v236, v[232:235], s[64:65] nt
	s_waitcnt vmcnt(16)
; #define LAS __attribute__((address_space(3)))
; __device__ __forceinline__ unsigned cvt_pk_bf16(float lo, float hi) { unsigned r; asm volatile("v_cvt_pk_bf16_f32 %0, %1, %2" : "=v"(r) : "v"(lo), "v"(hi)); return r; }
; #define LDS_WAIT() asm volatile("s_waitcnt lgkmcnt(0)" ::: "memory")
; template <bool NT = true> __device__ __forceinline__ void tr_finish(const TrDesc& d, const f32x4 (&v)[8], LAS float* scr, int lane) {
;     const int c = lane & 7;
;     f32x4 g0 = {1.f, 1.f, 1.f, 1.f}, g1 = {1.f, 1.f, 1.f, 1.f};
;     if (d.gain) { g0 = *(const f32x4*)(d.gain + 8 * c); g1 = *(const f32x4*)(d.gain + 8 * c + 4); }
; #pragma unroll
;     for (int i = 0; i < 8; ++i) { LAS float* w = scr + (8 * i + (lane >> 3)) * 33 + 4 * c; w[0] = v[i].x; w[1] = v[i].y; w[2] = v[i].z; w[3] = v[i].w; }
;     LDS_WAIT(); asm volatile("" ::: "memory");
; #pragma unroll
;     for (int j = 0; j < 4; ++j) { const int n = (lane >> 3) + 8 * j; const LAS float* s = scr + (8 * c) * 33 + n;
;         u32x4 o; o.x = cvt_pk_bf16(s[0 * 33] * g0.x, s[1 * 33] * g0.y); o.y = cvt_pk_bf16(s[2 * 33] * g0.z, s[3 * 33] * g0.w); o.z = cvt_pk_bf16(s[4 * 33] * g1.x, s[5 * 33] * g1.y); o.w = cvt_pk_bf16(s[6 * 33] * g1.z, s[7 * 33] * g1.w);
;         if (NT) __builtin_nontemporal_store(o, (u32x4*)(d.dst + (size_t)n * d.K + 8 * c)); else *(u32x4*)(d.dst + (size_t)n * d.K + 8 * c) = o; }
; template <class F, bool NT = true> __device__ __forceinline__ void tr_run(F item, int first, int step, int n, LAS float* scr, int lane) {
;     if (first >= n) return;
;     TrDesc da = item(first), db = da, dc = da; f32x4 va[8], vb[8], vc[8];
;     tr_load<NT>(da, va, lane);
;     if (first + step < n) { db = item(first + step); tr_load<NT>(db, vb, lane); }
;     for (int it = first; it < n; it += 3 * step) {
;         const bool h1 = it + step < n, h2 = it + 2 * step < n, h3 = it + 3 * step < n, h4 = it + 4 * step < n;
;         if (h2) { dc = item(it + 2 * step); tr_load<NT>(dc, vc, lane); }
;         tr_finish<NT>(da, va, scr, lane);
;         if (h3) { da = item(it + 3 * step); tr_load<NT>(da, va, lane); }
;         if (h1) tr_finish<NT>(db, vb, scr, lane);
;         if (h4) { db = item(it + 4 * step); tr_load<NT>(db, vb, lane); }
;         if (h2) tr_finish<NT>(dc, vc, scr, lane);
;     }
; }
	v_mul_f32_e32 v148, v220, v148
	v_mul_f32_e32 v149, v220, v149
	v_mul_f32_e32 v150, v220, v150
	v_mul_f32_e32 v151, v220, v151
	v_mul_f32_e32 v152, v221, v152
	v_mul_f32_e32 v153, v221, v153
	v_mul_f32_e32 v154, v221, v154
	v_mul_f32_e32 v155, v221, v155
	v_mul_f32_e32 v156, v222, v156
	v_mul_f32_e32 v157, v222, v157
	v_mul_f32_e32 v158, v222, v158
	v_mul_f32_e32 v159, v222, v159
	v_mul_f32_e32 v160, v223, v160
	v_mul_f32_e32 v161, v223, v161
	v_mul_f32_e32 v162, v223, v162
	v_mul_f32_e32 v163, v223, v163
	v_mul_f32_e32 v166, v224, v166
	v_mul_f32_e32 v167, v224, v167
	v_mul_f32_e32 v168, v224, v168
	v_mul_f32_e32 v169, v224, v169
	v_mul_f32_e32 v170, v225, v170
	v_mul_f32_e32 v171, v225, v171
	v_mul_f32_e32 v172, v225, v172
	v_mul_f32_e32 v173, v225, v173
	v_mul_f32_e32 v174, v226, v174
	v_mul_f32_e32 v175, v226, v175
	v_mul_f32_e32 v176, v226, v176
	v_mul_f32_e32 v177, v226, v177
	v_mul_f32_e32 v178, v227, v178
	v_mul_f32_e32 v179, v227, v179
	v_mul_f32_e32 v180, v227, v180
	v_mul_f32_e32 v181, v227, v181
	v_cvt_pk_bf16_f32 v228, v148, v152
	v_cvt_pk_bf16_f32 v229, v156, v160
	v_cvt_pk_bf16_f32 v230, v166, v170
	v_cvt_pk_bf16_f32 v231, v174, v178
	global_store_dwordx4 v214, v[228:231], s[66:67] nt
	v_cvt_pk_bf16_f32 v232, v149, v153
	v_cvt_pk_bf16_f32 v233, v157, v161
	v_cvt_pk_bf16_f32 v234, v167, v171
	v_cvt_pk_bf16_f32 v235, v175, v179
	global_store_dwordx4 v215, v[232:235], s[66:67] nt
	v_cvt_pk_bf16_f32 v228, v150, v154
	v_cvt_pk_bf16_f32 v229, v158, v162
	v_cvt_pk_bf16_f32 v230, v168, v172
	v_cvt_pk_bf16_f32 v231, v176, v180
	global_store_dwordx4 v219, v[228:231], s[66:67] nt
	v_cvt_pk_bf16_f32 v232, v151, v155
	v_cvt_pk_bf16_f32 v233, v159, v163
	v_cvt_pk_bf16_f32 v234, v169, v173
	v_cvt_pk_bf16_f32 v235, v177, v181
	global_store_dwordx4 v236, v[232:235], s[66:67] nt
	s_waitcnt vmcnt(12)
	v_mul_f32_e32 v182, v220, v182
	v_mul_f32_e32 v183, v220, v183
	v_mul_f32_e32 v184, v220, v184
	v_mul_f32_e32 v185, v220, v185
	v_mul_f32_e32 v186, v221, v186
	v_mul_f32_e32 v187, v221, v187
	v_mul_f32_e32 v188, v221, v188
	v_mul_f32_e32 v189, v221, v189
	v_mul_f32_e32 v190, v222, v190
	v_mul_f32_e32 v191, v222, v191
	v_mul_f32_e32 v192, v222, v192
	v_mul_f32_e32 v193, v222, v193
	v_mul_f32_e32 v194, v223, v194
	v_mul_f32_e32 v195, v223, v195
	v_mul_f32_e32 v196, v223, v196
	v_mul_f32_e32 v197, v223, v197
	v_mul_f32_e32 v198, v224, v198
	v_mul_f32_e32 v199, v224, v199
	v_mul_f32_e32 v200, v224, v200
	v_mul_f32_e32 v201, v224, v201
	v_mul_f32_e32 v202, v225, v202
	v_mul_f32_e32 v203, v225, v203
	v_mul_f32_e32 v204, v225, v204
	v_mul_f32_e32 v205, v225, v205
	v_mul_f32_e32 v206, v226, v206
	v_mul_f32_e32 v207, v226, v207
	v_mul_f32_e32 v208, v226, v208
	v_mul_f32_e32 v209, v226, v209
	v_mul_f32_e32 v210, v227, v210
	v_mul_f32_e32 v211, v227, v211
	v_mul_f32_e32 v212, v227, v212
	v_mul_f32_e32 v213, v227, v213
	v_cvt_pk_bf16_f32 v228, v182, v186
	v_cvt_pk_bf16_f32 v229, v190, v194
	v_cvt_pk_bf16_f32 v230, v198, v202
	v_cvt_pk_bf16_f32 v231, v206, v210
	global_store_dwordx4 v214, v[228:231], s[68:69] nt
	v_cvt_pk_bf16_f32 v232, v183, v187
	v_cvt_pk_bf16_f32 v233, v191, v195
	v_cvt_pk_bf16_f32 v234, v199, v203
	v_cvt_pk_bf16_f32 v235, v207, v211
	global_store_dwordx4 v215, v[232:235], s[68:69] nt
	v_cvt_pk_bf16_f32 v228, v184, v188
	v_cvt_pk_bf16_f32 v229, v192, v196
	v_cvt_pk_bf16_f32 v230, v200, v204
	v_cvt_pk_bf16_f32 v231, v208, v212
	global_store_dwordx4 v219, v[228:231], s[68:69] nt
	v_cvt_pk_bf16_f32 v232, v185, v189
	v_cvt_pk_bf16_f32 v233, v193, v197
	v_cvt_pk_bf16_f32 v234, v201, v205
	v_cvt_pk_bf16_f32 v235, v209, v213
	global_store_dwordx4 v236, v[232:235], s[68:69] nt
	s_branch .Lpz_ret
.Lpz_nogain:
	global_load_dwordx4 v[6:9], v2, s[60:61] offset:0 nt
	global_load_dwordx4 v[10:13], v120, s[60:61] offset:0 nt
	global_load_dwordx4 v[14:17], v121, s[60:61] offset:0 nt
	global_load_dwordx4 v[18:21], v126, s[60:61] offset:0 nt
	global_load_dwordx4 v[22:25], v144, s[60:61] offset:0 nt
	global_load_dwordx4 v[26:29], v145, s[60:61] offset:0 nt
	global_load_dwordx4 v[30:33], v147, s[60:61] offset:0 nt
	global_load_dwordx4 v[66:69], v165, s[60:61] offset:0 nt
	global_load_dwordx4 v[100:103], v2, s[60:61] offset:128 nt
	global_load_dwordx4 v[104:107], v120, s[60:61] offset:128 nt
	global_load_dwordx4 v[108:111], v121, s[60:61] offset:128 nt
	global_load_dwordx4 v[112:115], v126, s[60:61] offset:128 nt
	global_load_dwordx4 v[116:119], v144, s[60:61] offset:128 nt
	global_load_dwordx4 v[132:135], v145, s[60:61] offset:128 nt
	global_load_dwordx4 v[136:139], v147, s[60:61] offset:128 nt
	global_load_dwordx4 v[140:143], v165, s[60:61] offset:128 nt
	global_load_dwordx4 v[148:151], v2, s[60:61] offset:256 nt
	global_load_dwordx4 v[152:155], v120, s[60:61] offset:256 nt
	global_load_dwordx4 v[156:159], v121, s[60:61] offset:256 nt
	global_load_dwordx4 v[160:163], v126, s[60:61] offset:256 nt
	global_load_dwordx4 v[166:169], v144, s[60:61] offset:256 nt
	global_load_dwordx4 v[170:173], v145, s[60:61] offset:256 nt
	global_load_dwordx4 v[174:177], v147, s[60:61] offset:256 nt
	global_load_dwordx4 v[178:181], v165, s[60:61] offset:256 nt
	global_load_dwordx4 v[182:185], v2, s[60:61] offset:384 nt
	global_load_dwordx4 v[186:189], v120, s[60:61] offset:384 nt
	global_load_dwordx4 v[190:193], v121, s[60:61] offset:384 nt
	global_load_dwordx4 v[194:197], v126, s[60:61] offset:384 nt
	global_load_dwordx4 v[198:201], v144, s[60:61] offset:384 nt
	global_load_dwordx4 v[202:205], v145, s[60:61] offset:384 nt
	global_load_dwordx4 v[206:209], v147, s[60:61] offset:384 nt
	global_load_dwordx4 v[210:213], v165, s[60:61] offset:384 nt
	s_add_u32 s60, s60, s70
	s_addc_u32 s61, s61, s71
	s_cmp_eq_u32 s74, 1
	s_cbranch_scc1 .Lpz_n_last
; #define LAS __attribute__((address_space(3)))
; __device__ __forceinline__ unsigned cvt_pk_bf16(float lo, float hi) { unsigned r; asm volatile("v_cvt_pk_bf16_f32 %0, %1, %2" : "=v"(r) : "v"(lo), "v"(hi)); return r; }
; #define LDS_WAIT() asm volatile("s_waitcnt lgkmcnt(0)" ::: "memory")
; __device__ __forceinline__ unsigned cvt_pk_bf16(float lo, float hi) { unsigned r; asm volatile("v_cvt_pk_bf16_f32 %0, %1, %2" : "=v"(r) : "v"(lo), "v"(hi)); return r; }
; template <bool NT = true> __device__ __forceinline__ void tr_finish(const TrDesc& d, const f32x4 (&v)[8], LAS float* scr, int lane) {
;     const int c = lane & 7;
;     f32x4 g0 = {1.f, 1.f, 1.f, 1.f}, g1 = {1.f, 1.f, 1.f, 1.f};
;     if (d.gain) { g0 = *(const f32x4*)(d.gain + 8 * c); g1 = *(const f32x4*)(d.gain + 8 * c + 4); }
; #pragma unroll
;     for (int i = 0; i < 8; ++i) { LAS float* w = scr + (8 * i + (lane >> 3)) * 33 + 4 * c; w[0] = v[i].x; w[1] = v[i].y; w[2] = v[i].z; w[3] = v[i].w; }
;     LDS_WAIT(); asm volatile("" ::: "memory");
; #pragma unroll
;     for (int j = 0; j < 4; ++j) { const int n = (lane >> 3) + 8 * j; const LAS float* s = scr + (8 * c) * 33 + n;
;         u32x4 o; o.x = cvt_pk_bf16(s[0 * 33] * g0.x, s[1 * 33] * g0.y); o.y = cvt_pk_bf16(s[2 * 33] * g0.z, s[3 * 33] * g0.w); o.z = cvt_pk_bf16(s[4 * 33] * g1.x, s[5 * 33] * g1.y); o.w = cvt_pk_bf16(s[6 * 33] * g1.z, s[7 * 33] * g1.w);
;         if (NT) __builtin_nontemporal_store(o, (u32x4*)(d.dst + (size_t)n * d.K + 8 * c)); else *(u32x4*)(d.dst + (size_t)n * d.K + 8 * c) = o; }
; template <class F, bool NT = true> __device__ __forceinline__ void tr_run(F item, int first, int step, int n, LAS float* scr, int lane) {
;     ...
;     for (int it = first; it < n; it += 3 * step) {
;         const bool h1 = it + step < n, h2 = it + 2 * step < n, h3 = it + 3 * step < n, h4 = it + 4 * step < n;
;         if (h2) { dc = item(it + 2 * step); tr_load<NT>(dc, vc, lane); }
;         tr_finish<NT>(da, va, scr, lane);
;         if (h3) { da = item(it + 3 * step); tr_load<NT>(da, va, lane); }
;         if (h1) tr_finish<NT>(db, vb, scr, lane);
;         if (h4) { db = item(it + 4 * step); tr_load<NT>(db, vb, lane); }
;         if (h2) tr_finish<NT>(dc, vc, scr, lane);
;     }
	s_waitcnt vmcnt(24)
	v_cvt_pk_bf16_f32 v228, v6, v10
	v_cvt_pk_bf16_f32 v229, v14, v18
	v_cvt_pk_bf16_f32 v230, v22, v26
	v_cvt_pk_bf16_f32 v231, v30, v66
	global_store_dwordx4 v214, v[228:231], s[62:63] nt
	v_cvt_pk_bf16_f32 v232, v7, v11
	v_cvt_pk_bf16_f32 v233, v15, v19
	v_cvt_pk_bf16_f32 v234, v23, v27
	v_cvt_pk_bf16_f32 v235, v31, v67
	global_store_dwordx4 v215, v[232:235], s[62:63] nt
	v_cvt_pk_bf16_f32 v228, v8, v12
	v_cvt_pk_bf16_f32 v229, v16, v20
	v_cvt_pk_bf16_f32 v230, v24, v28
	v_cvt_pk_bf16_f32 v231, v32, v68
	global_store_dwordx4 v219, v[228:231], s[62:63] nt
	v_cvt_pk_bf16_f32 v232, v9, v13
	v_cvt_pk_bf16_f32 v233, v17, v21
	v_cvt_pk_bf16_f32 v234, v25, v29
	v_cvt_pk_bf16_f32 v235, v33, v69
	global_store_dwordx4 v236, v[232:235], s[62:63] nt
	global_load_dwordx4 v[6:9], v2, s[60:61] offset:0 nt
	global_load_dwordx4 v[10:13], v120, s[60:61] offset:0 nt
	global_load_dwordx4 v[14:17], v121, s[60:61] offset:0 nt
	global_load_dwordx4 v[18:21], v126, s[60:61] offset:0 nt
	global_load_dwordx4 v[22:25], v144, s[60:61] offset:0 nt
	global_load_dwordx4 v[26:29], v145, s[60:61] offset:0 nt
	global_load_dwordx4 v[30:33], v147, s[60:61] offset:0 nt
	global_load_dwordx4 v[66:69], v165, s[60:61] offset:0 nt
	s_add_u32 s62, s62, s72
	s_addc_u32 s63, s63, s73
	s_waitcnt vmcnt(28)
	v_cvt_pk_bf16_f32 v228, v100, v104
	v_cvt_pk_bf16_f32 v229, v108, v112
	v_cvt_pk_bf16_f32 v230, v116, v132
	v_cvt_pk_bf16_f32 v231, v136, v140
	global_store_dwordx4 v214, v[228:231], s[64:65] nt
	v_cvt_pk_bf16_f32 v232, v101, v105
	v_cvt_pk_bf16_f32 v233, v109, v113
	v_cvt_pk_bf16_f32 v234, v117, v133
	v_cvt_pk_bf16_f32 v235, v137, v141
	global_store_dwordx4 v215, v[232:235], s[64:65] nt
	v_cvt_pk_bf16_f32 v228, v102, v106
	v_cvt_pk_bf16_f32 v229, v110, v114
	v_cvt_pk_bf16_f32 v230, v118, v134
	v_cvt_pk_bf16_f32 v231, v138, v142
	global_store_dwordx4 v219, v[228:231], s[64:65] nt
	v_cvt_pk_bf16_f32 v232, v103, v107
	v_cvt_pk_bf16_f32 v233, v111, v115
	v_cvt_pk_bf16_f32 v234, v119, v135
	v_cvt_pk_bf16_f32 v235, v139, v143
	global_store_dwordx4 v236, v[232:235], s[64:65] nt
	global_load_dwordx4 v[100:103], v2, s[60:61] offset:128 nt
	global_load_dwordx4 v[104:107], v120, s[60:61] offset:128 nt
	global_load_dwordx4 v[108:111], v121, s[60:61] offset:128 nt
	global_load_dwordx4 v[112:115], v126, s[60:61] offset:128 nt
	global_load_dwordx4 v[116:119], v144, s[60:61] offset:128 nt
	global_load_dwordx4 v[132:135], v145, s[60:61] offset:128 nt
	global_load_dwordx4 v[136:139], v147, s[60:61] offset:128 nt
	global_load_dwordx4 v[140:143], v165, s[60:61] offset:128 nt
	s_add_u32 s64, s64, s72
	s_addc_u32 s65, s65, s73
	s_waitcnt vmcnt(32)
	v_cvt_pk_bf16_f32 v228, v148, v152
	v_cvt_pk_bf16_f32 v229, v156, v160
	v_cvt_pk_bf16_f32 v230, v166, v170
	v_cvt_pk_bf16_f32 v231, v174, v178
	global_store_dwordx4 v214, v[228:231], s[66:67] nt
	v_cvt_pk_bf16_f32 v232, v149, v153
	v_cvt_pk_bf16_f32 v233, v157, v161
	v_cvt_pk_bf16_f32 v234, v167, v171
	v_cvt_pk_bf16_f32 v235, v175, v179
	global_store_dwordx4 v215, v[232:235], s[66:67] nt
	v_cvt_pk_bf16_f32 v228, v150, v154
	v_cvt_pk_bf16_f32 v229, v158, v162
	v_cvt_pk_bf16_f32 v230, v168, v172
	v_cvt_pk_bf16_f32 v231, v176, v180
	global_store_dwordx4 v219, v[228:231], s[66:67] nt
	v_cvt_pk_bf16_f32 v232, v151, v155
	v_cvt_pk_bf16_f32 v233, v159, v163
	v_cvt_pk_bf16_f32 v234, v169, v173
	v_cvt_pk_bf16_f32 v235, v177, v181
	global_store_dwordx4 v236, v[232:235], s[66:67] nt
	global_load_dwordx4 v[148:151], v2, s[60:61] offset:256 nt
	global_load_dwordx4 v[152:155], v120, s[60:61] offset:256 nt
	global_load_dwordx4 v[156:159], v121, s[60:61] offset:256 nt
	global_load_dwordx4 v[160:163], v126, s[60:61] offset:256 nt
	global_load_dwordx4 v[166:169], v144, s[60:61] offset:256 nt
	global_load_dwordx4 v[170:173], v145, s[60:61] offset:256 nt
	global_load_dwordx4 v[174:177], v147, s[60:61] offset:256 nt
	global_load_dwordx4 v[178:181], v165, s[60:61] offset:256 nt
	s_add_u32 s66, s66, s72
	s_addc_u32 s67, s67, s73
	s_waitcnt vmcnt(36)
	v_cvt_pk_bf16_f32 v228, v182, v186
	v_cvt_pk_bf16_f32 v229, v190, v194
	v_cvt_pk_bf16_f32 v230, v198, v202
	v_cvt_pk_bf16_f32 v231, v206, v210
	global_store_dwordx4 v214, v[228:231], s[68:69] nt
	v_cvt_pk_bf16_f32 v232, v183, v187
	v_cvt_pk_bf16_f32 v233, v191, v195
	v_cvt_pk_bf16_f32 v234, v199, v203
	v_cvt_pk_bf16_f32 v235, v207, v211
	global_store_dwordx4 v215, v[232:235], s[68:69] nt
	v_cvt_pk_bf16_f32 v228, v184, v188
	v_cvt_pk_bf16_f32 v229, v192, v196
	v_cvt_pk_bf16_f32 v230, v200, v204
	v_cvt_pk_bf16_f32 v231, v208, v212
	global_store_dwordx4 v219, v[228:231], s[68:69] nt
	v_cvt_pk_bf16_f32 v232, v185, v189
	v_cvt_pk_bf16_f32 v233, v193, v197
	v_cvt_pk_bf16_f32 v234, v201, v205
	v_cvt_pk_bf16_f32 v235, v209, v213
	global_store_dwordx4 v236, v[232:235], s[68:69] nt
	global_load_dwordx4 v[182:185], v2, s[60:61] offset:384 nt
	global_load_dwordx4 v[186:189], v120, s[60:61] offset:384 nt
	global_load_dwordx4 v[190:193], v121, s[60:61] offset:384 nt
	global_load_dwordx4 v[194:197], v126, s[60:61] offset:384 nt
	global_load_dwordx4 v[198:201], v144, s[60:61] offset:384 nt
	global_load_dwordx4 v[202:205], v145, s[60:61] offset:384 nt
	global_load_dwordx4 v[206:209], v147, s[60:61] offset:384 nt
	global_load_dwordx4 v[210:213], v165, s[60:61] offset:384 nt
	s_add_u32 s68, s68, s72
	s_addc_u32 s69, s69, s73
	s_add_u32 s60, s60, s70
	s_addc_u32 s61, s61, s71
	s_sub_i32 s74, s74, 1
	s_cmp_eq_u32 s74, 1
	s_cbranch_scc1 .Lpz_n_last
; template <bool NT = true> __device__ __forceinline__ void tr_load(const TrDesc& d, f32x4 (&v)[8], int lane) {
;     const float* sp = d.src + (size_t)(lane >> 3) * d.ldn + 4 * (lane & 7);
; #pragma unroll
;     for (int i = 0; i < 8; ++i) v[i] = NT ? __builtin_nontemporal_load((const f32x4*)(sp + (size_t)(8 * i) * d.ldn)) : *(const f32x4*)(sp + (size_t)(8 * i) * d.ldn);
; }
; template <bool NT = true> __device__ __forceinline__ void tr_finish(const TrDesc& d, const f32x4 (&v)[8], LAS float* scr, int lane) {
;     const int c = lane & 7;
;     f32x4 g0 = {1.f, 1.f, 1.f, 1.f}, g1 = {1.f, 1.f, 1.f, 1.f};
;     if (d.gain) { g0 = *(const f32x4*)(d.gain + 8 * c); g1 = *(const f32x4*)(d.gain + 8 * c + 4); }
; #pragma unroll
;     for (int i = 0; i < 8; ++i) { LAS float* w = scr + (8 * i + (lane >> 3)) * 33 + 4 * c; w[0] = v[i].x; w[1] = v[i].y; w[2] = v[i].z; w[3] = v[i].w; }
;     LDS_WAIT(); asm volatile("" ::: "memory");
; #pragma unroll
;     for (int j = 0; j < 4; ++j) { const int n = (lane >> 3) + 8 * j; const LAS float* s = scr + (8 * c) * 33 + n;
;         u32x4 o; o.x = cvt_pk_bf16(s[0 * 33] * g0.x, s[1 * 33] * g0.y); o.y = cvt_pk_bf16(s[2 * 33] * g0.z, s[3 * 33] * g0.w); o.z = cvt_pk_bf16(s[4 * 33] * g1.x, s[5 * 33] * g1.y); o.w = cvt_pk_bf16(s[6 * 33] * g1.z, s[7 * 33] * g1.w);
;         if (NT) __builtin_nontemporal_store(o, (u32x4*)(d.dst + (size_t)n * d.K + 8 * c)); else *(u32x4*)(d.dst + (size_t)n * d.K + 8 * c) = o; }
;     LDS_WAIT(); asm volatile("" ::: "memory");
; }
; template <class F, bool NT = true> __device__ __forceinline__ void tr_run(F item, int first, int step, int n, LAS float* scr, int lane) {
;     if (first >= n) return;
;     TrDesc da = item(first), db = da, dc = da; f32x4 va[8], vb[8], vc[8];
;     tr_load<NT>(da, va, lane);
;     if (first + step < n) { db = item(first + step); tr_load<NT>(db, vb, lane); }
;     for (int it = first; it < n; it += 3 * step) {
;         const bool h1 = it + step < n, h2 = it + 2 * step < n, h3 = it + 3 * step < n, h4 = it + 4 * step < n;
;         if (h2) { dc = item(it + 2 * step); tr_load<NT>(dc, vc, lane); }
;         tr_finish<NT>(da, va, scr, lane);
;         if (h3) { da = item(it + 3 * step); tr_load<NT>(da, va, lane); }
;         if (h1) tr_finish<NT>(db, vb, scr, lane);
;         if (h4) { db = item(it + 4 * step); tr_load<NT>(db, vb, lane); }
.Lpz_n_steady:
	s_waitcnt vmcnt(36)
	v_cvt_pk_bf16_f32 v228, v6, v10
	v_cvt_pk_bf16_f32 v229, v14, v18
	v_cvt_pk_bf16_f32 v230, v22, v26
	v_cvt_pk_bf16_f32 v231, v30, v66
	global_store_dwordx4 v214, v[228:231], s[62:63] nt
	v_cvt_pk_bf16_f32 v232, v7, v11
	v_cvt_pk_bf16_f32 v233, v15, v19
	v_cvt_pk_bf16_f32 v234, v23, v27
	v_cvt_pk_bf16_f32 v235, v31, v67
	global_store_dwordx4 v215, v[232:235], s[62:63] nt
	v_cvt_pk_bf16_f32 v228, v8, v12
	v_cvt_pk_bf16_f32 v229, v16, v20
	v_cvt_pk_bf16_f32 v230, v24, v28
	v_cvt_pk_bf16_f32 v231, v32, v68
	global_store_dwordx4 v219, v[228:231], s[62:63] nt
	v_cvt_pk_bf16_f32 v232, v9, v13
	v_cvt_pk_bf16_f32 v233, v17, v21
	v_cvt_pk_bf16_f32 v234, v25, v29
	v_cvt_pk_bf16_f32 v235, v33, v69
	global_store_dwordx4 v236, v[232:235], s[62:63] nt
	global_load_dwordx4 v[6:9], v2, s[60:61] offset:0 nt
	global_load_dwordx4 v[10:13], v120, s[60:61] offset:0 nt
	global_load_dwordx4 v[14:17], v121, s[60:61] offset:0 nt
	global_load_dwordx4 v[18:21], v126, s[60:61] offset:0 nt
	global_load_dwordx4 v[22:25], v144, s[60:61] offset:0 nt
	global_load_dwordx4 v[26:29], v145, s[60:61] offset:0 nt
	global_load_dwordx4 v[30:33], v147, s[60:61] offset:0 nt
	global_load_dwordx4 v[66:69], v165, s[60:61] offset:0 nt
	s_add_u32 s62, s62, s72
	s_addc_u32 s63, s63, s73
	s_waitcnt vmcnt(36)
	v_cvt_pk_bf16_f32 v228, v100, v104
	v_cvt_pk_bf16_f32 v229, v108, v112
	v_cvt_pk_bf16_f32 v230, v116, v132
	v_cvt_pk_bf16_f32 v231, v136, v140
	global_store_dwordx4 v214, v[228:231], s[64:65] nt
	v_cvt_pk_bf16_f32 v232, v101, v105
	v_cvt_pk_bf16_f32 v233, v109, v113
	v_cvt_pk_bf16_f32 v234, v117, v133
	v_cvt_pk_bf16_f32 v235, v137, v141
	global_store_dwordx4 v215, v[232:235], s[64:65] nt
	v_cvt_pk_bf16_f32 v228, v102, v106
	v_cvt_pk_bf16_f32 v229, v110, v114
	v_cvt_pk_bf16_f32 v230, v118, v134
	v_cvt_pk_bf16_f32 v231, v138, v142
	global_store_dwordx4 v219, v[228:231], s[64:65] nt
	v_cvt_pk_bf16_f32 v232, v103, v107
	v_cvt_pk_bf16_f32 v233, v111, v115
	v_cvt_pk_bf16_f32 v234, v119, v135
	v_cvt_pk_bf16_f32 v235, v139, v143
	global_store_dwordx4 v236, v[232:235], s[64:65] nt
	global_load_dwordx4 v[100:103], v2, s[60:61] offset:128 nt
	global_load_dwordx4 v[104:107], v120, s[60:61] offset:128 nt
	global_load_dwordx4 v[108:111], v121, s[60:61] offset:128 nt
	global_load_dwordx4 v[112:115], v126, s[60:61] offset:128 nt
	global_load_dwordx4 v[116:119], v144, s[60:61] offset:128 nt
	global_load_dwordx4 v[132:135], v145, s[60:61] offset:128 nt
	global_load_dwordx4 v[136:139], v147, s[60:61] offset:128 nt
	global_load_dwordx4 v[140:143], v165, s[60:61] offset:128 nt
	s_add_u32 s64, s64, s72
	s_addc_u32 s65, s65, s73
	s_waitcnt vmcnt(36)
	v_cvt_pk_bf16_f32 v228, v148, v152
	v_cvt_pk_bf16_f32 v229, v156, v160
	v_cvt_pk_bf16_f32 v230, v166, v170
	v_cvt_pk_bf16_f32 v231, v174, v178
	global_store_dwordx4 v214, v[228:231], s[66:67] nt
	v_cvt_pk_bf16_f32 v232, v149, v153
	v_cvt_pk_bf16_f32 v233, v157, v161
	v_cvt_pk_bf16_f32 v234, v167, v171
	v_cvt_pk_bf16_f32 v235, v175, v179
	global_store_dwordx4 v215, v[232:235], s[66:67] nt
	v_cvt_pk_bf16_f32 v228, v150, v154
	v_cvt_pk_bf16_f32 v229, v158, v162
	v_cvt_pk_bf16_f32 v230, v168, v172
	v_cvt_pk_bf16_f32 v231, v176, v180
	global_store_dwordx4 v219, v[228:231], s[66:67] nt
	v_cvt_pk_bf16_f32 v232, v151, v155
	v_cvt_pk_bf16_f32 v233, v159, v163
	v_cvt_pk_bf16_f32 v234, v169, v173
	v_cvt_pk_bf16_f32 v235, v177, v181
	global_store_dwordx4 v236, v[232:235], s[66:67] nt
	global_load_dwordx4 v[148:151], v2, s[60:61] offset:256 nt
	global_load_dwordx4 v[152:155], v120, s[60:61] offset:256 nt
	global_load_dwordx4 v[156:159], v121, s[60:61] offset:256 nt
	global_load_dwordx4 v[160:163], v126, s[60:61] offset:256 nt
	global_load_dwordx4 v[166:169], v144, s[60:61] offset:256 nt
	global_load_dwordx4 v[170:173], v145, s[60:61] offset:256 nt
	global_load_dwordx4 v[174:177], v147, s[60:61] offset:256 nt
	global_load_dwordx4 v[178:181], v165, s[60:61] offset:256 nt
	s_add_u32 s66, s66, s72
	s_addc_u32 s67, s67, s73
	s_waitcnt vmcnt(36)
	v_cvt_pk_bf16_f32 v228, v182, v186
	v_cvt_pk_bf16_f32 v229, v190, v194
	v_cvt_pk_bf16_f32 v230, v198, v202
	v_cvt_pk_bf16_f32 v231, v206, v210
	global_store_dwordx4 v214, v[228:231], s[68:69] nt
	v_cvt_pk_bf16_f32 v232, v183, v187
	v_cvt_pk_bf16_f32 v233, v191, v195
	v_cvt_pk_bf16_f32 v234, v199, v203
	v_cvt_pk_bf16_f32 v235, v207, v211
	global_store_dwordx4 v215, v[232:235], s[68:69] nt
	v_cvt_pk_bf16_f32 v228, v184, v188
	v_cvt_pk_bf16_f32 v229, v192, v196
	v_cvt_pk_bf16_f32 v230, v200, v204
	v_cvt_pk_bf16_f32 v231, v208, v212
	global_store_dwordx4 v219, v[228:231], s[68:69] nt
	v_cvt_pk_bf16_f32 v232, v185, v189
	v_cvt_pk_bf16_f32 v233, v193, v197
	v_cvt_pk_bf16_f32 v234, v201, v205
	v_cvt_pk_bf16_f32 v235, v209, v213
	global_store_dwordx4 v236, v[232:235], s[68:69] nt
	global_load_dwordx4 v[182:185], v2, s[60:61] offset:384 nt
	global_load_dwordx4 v[186:189], v120, s[60:61] offset:384 nt
	global_load_dwordx4 v[190:193], v121, s[60:61] offset:384 nt
	global_load_dwordx4 v[194:197], v126, s[60:61] offset:384 nt
	global_load_dwordx4 v[198:201], v144, s[60:61] offset:384 nt
	global_load_dwordx4 v[202:205], v145, s[60:61] offset:384 nt
	global_load_dwordx4 v[206:209], v147, s[60:61] offset:384 nt
	global_load_dwordx4 v[210:213], v165, s[60:61] offset:384 nt
	s_add_u32 s68, s68, s72
	s_addc_u32 s69, s69, s73
	s_add_u32 s60, s60, s70
	s_addc_u32 s61, s61, s71
	s_sub_i32 s74, s74, 1
	s_cmp_eq_u32 s74, 1
	s_cbranch_scc0 .Lpz_n_steady
; #define LAS __attribute__((address_space(3)))
; __device__ __forceinline__ unsigned cvt_pk_bf16(float lo, float hi) { unsigned r; asm volatile("v_cvt_pk_bf16_f32 %0, %1, %2" : "=v"(r) : "v"(lo), "v"(hi)); return r; }
; #define LDS_WAIT() asm volatile("s_waitcnt lgkmcnt(0)" ::: "memory")
; __device__ __forceinline__ unsigned cvt_pk_bf16(float lo, float hi) { unsigned r; asm volatile("v_cvt_pk_bf16_f32 %0, %1, %2" : "=v"(r) : "v"(lo), "v"(hi)); return r; }
; __device__ __forceinline__ unsigned xb_add(unsigned* p, unsigned v) { return __hip_atomic_fetch_add(p, v, __ATOMIC_RELAXED, __HIP_MEMORY_SCOPE_AGENT); }
; __device__ __forceinline__ void xcd_barrier(const XcdBarrier& b) {
;     asm volatile("s_waitcnt vmcnt(0)" ::: "memory");
;     __syncthreads();
;     if (threadIdx.x == 0) {
;         unsigned* bar = b.bar;
;         __builtin_amdgcn_s_waitcnt(0);
;         unsigned nloc = b.st[0], nx = b.st[1];
;         if (nloc == 0u) { xcd_barrier_complete(bar, b.x, nloc, nx); b.st[0] = nloc; b.st[1] = nx; }
;         const unsigned old = xb_add(&bar[XB_XSUB(b.x)], 1u);
; template <bool NT = true> __device__ __forceinline__ void tr_finish(const TrDesc& d, const f32x4 (&v)[8], LAS float* scr, int lane) {
;     const int c = lane & 7;
;     f32x4 g0 = {1.f, 1.f, 1.f, 1.f}, g1 = {1.f, 1.f, 1.f, 1.f};
;     if (d.gain) { g0 = *(const f32x4*)(d.gain + 8 * c); g1 = *(const f32x4*)(d.gain + 8 * c + 4); }
; #pragma unroll
;     for (int i = 0; i < 8; ++i) { LAS float* w = scr + (8 * i + (lane >> 3)) * 33 + 4 * c; w[0] = v[i].x; w[1] = v[i].y; w[2] = v[i].z; w[3] = v[i].w; }
;     LDS_WAIT(); asm volatile("" ::: "memory");
; #pragma unroll
;     for (int j = 0; j < 4; ++j) { const int n = (lane >> 3) + 8 * j; const LAS float* s = scr + (8 * c) * 33 + n;
;         u32x4 o; o.x = cvt_pk_bf16(s[0 * 33] * g0.x, s[1 * 33] * g0.y); o.y = cvt_pk_bf16(s[2 * 33] * g0.z, s[3 * 33] * g0.w); o.z = cvt_pk_bf16(s[4 * 33] * g1.x, s[5 * 33] * g1.y); o.w = cvt_pk_bf16(s[6 * 33] * g1.z, s[7 * 33] * g1.w);
;         if (NT) __builtin_nontemporal_store(o, (u32x4*)(d.dst + (size_t)n * d.K + 8 * c)); else *(u32x4*)(d.dst + (size_t)n * d.K + 8 * c) = o; }
;     LDS_WAIT(); asm volatile("" ::: "memory");
; }
.Lpz_n_last:
	s_waitcnt vmcnt(24)
	v_cvt_pk_bf16_f32 v228, v6, v10
	v_cvt_pk_bf16_f32 v229, v14, v18
	v_cvt_pk_bf16_f32 v230, v22, v26
	v_cvt_pk_bf16_f32 v231, v30, v66
	global_store_dwordx4 v214, v[228:231], s[62:63] nt
	v_cvt_pk_bf16_f32 v232, v7, v11
	v_cvt_pk_bf16_f32 v233, v15, v19
	v_cvt_pk_bf16_f32 v234, v23, v27
	v_cvt_pk_bf16_f32 v235, v31, v67
	global_store_dwordx4 v215, v[232:235], s[62:63] nt
	v_cvt_pk_bf16_f32 v228, v8, v12
	v_cvt_pk_bf16_f32 v229, v16, v20
	v_cvt_pk_bf16_f32 v230, v24, v28
	v_cvt_pk_bf16_f32 v231, v32, v68
	global_store_dwordx4 v219, v[228:231], s[62:63] nt
	v_cvt_pk_bf16_f32 v232, v9, v13
	v_cvt_pk_bf16_f32 v233, v17, v21
	v_cvt_pk_bf16_f32 v234, v25, v29
	v_cvt_pk_bf16_f32 v235, v33, v69
	global_store_dwordx4 v236, v[232:235], s[62:63] nt
	s_waitcnt vmcnt(20)
	v_cvt_pk_bf16_f32 v228, v100, v104
	v_cvt_pk_bf16_f32 v229, v108, v112
	v_cvt_pk_bf16_f32 v230, v116, v132
	v_cvt_pk_bf16_f32 v231, v136, v140
	global_store_dwordx4 v214, v[228:231], s[64:65] nt
	v_cvt_pk_bf16_f32 v232, v101, v105
	v_cvt_pk_bf16_f32 v233, v109, v113
	v_cvt_pk_bf16_f32 v234, v117, v133
	v_cvt_pk_bf16_f32 v235, v137, v141
	global_store_dwordx4 v215, v[232:235], s[64:65] nt
	v_cvt_pk_bf16_f32 v228, v102, v106
	v_cvt_pk_bf16_f32 v229, v110, v114
	v_cvt_pk_bf16_f32 v230, v118, v134
	v_cvt_pk_bf16_f32 v231, v138, v142
	global_store_dwordx4 v219, v[228:231], s[64:65] nt
	v_cvt_pk_bf16_f32 v232, v103, v107
	v_cvt_pk_bf16_f32 v233, v111, v115
	v_cvt_pk_bf16_f32 v234, v119, v135
	v_cvt_pk_bf16_f32 v235, v139, v143
	global_store_dwordx4 v236, v[232:235], s[64:65] nt
	s_waitcnt vmcnt(16)
	v_cvt_pk_bf16_f32 v228, v148, v152
	v_cvt_pk_bf16_f32 v229, v156, v160
	v_cvt_pk_bf16_f32 v230, v166, v170
	v_cvt_pk_bf16_f32 v231, v174, v178
	global_store_dwordx4 v214, v[228:231], s[66:67] nt
	v_cvt_pk_bf16_f32 v232, v149, v153
	v_cvt_pk_bf16_f32 v233, v157, v161
	v_cvt_pk_bf16_f32 v234, v167, v171
	v_cvt_pk_bf16_f32 v235, v175, v179
	global_store_dwordx4 v215, v[232:235], s[66:67] nt
	v_cvt_pk_bf16_f32 v228, v150, v154
	v_cvt_pk_bf16_f32 v229, v158, v162
	v_cvt_pk_bf16_f32 v230, v168, v172
	v_cvt_pk_bf16_f32 v231, v176, v180
	global_store_dwordx4 v219, v[228:231], s[66:67] nt
	v_cvt_pk_bf16_f32 v232, v151, v155
	v_cvt_pk_bf16_f32 v233, v159, v163
	v_cvt_pk_bf16_f32 v234, v169, v173
	v_cvt_pk_bf16_f32 v235, v177, v181
	global_store_dwordx4 v236, v[232:235], s[66:67] nt
	s_waitcnt vmcnt(12)
	v_cvt_pk_bf16_f32 v228, v182, v186
	v_cvt_pk_bf16_f32 v229, v190, v194
	v_cvt_pk_bf16_f32 v230, v198, v202
	v_cvt_pk_bf16_f32 v231, v206, v210
	global_store_dwordx4 v214, v[228:231], s[68:69] nt
	v_cvt_pk_bf16_f32 v232, v183, v187
	v_cvt_pk_bf16_f32 v233, v191, v195
	v_cvt_pk_bf16_f32 v234, v199, v203
	v_cvt_pk_bf16_f32 v235, v207, v211
	global_store_dwordx4 v215, v[232:235], s[68:69] nt
	v_cvt_pk_bf16_f32 v228, v184, v188
	v_cvt_pk_bf16_f32 v229, v192, v196
	v_cvt_pk_bf16_f32 v230, v200, v204
	v_cvt_pk_bf16_f32 v231, v208, v212
	global_store_dwordx4 v219, v[228:231], s[68:69] nt
	v_cvt_pk_bf16_f32 v232, v185, v189
	v_cvt_pk_bf16_f32 v233, v193, v197
	v_cvt_pk_bf16_f32 v234, v201, v205
	v_cvt_pk_bf16_f32 v235, v209, v213
	global_store_dwordx4 v236, v[232:235], s[68:69] nt
	s_branch .Lpz_ret
.Lpz_ret:
	s_cmp_eq_u32 s75, 0
	s_cbranch_scc1 .Lpz_back_0
	s_cmp_eq_u32 s75, 1
	s_cbranch_scc1 .Lpz_back_1
	s_cmp_eq_u32 s75, 2
	s_cbranch_scc1 .Lpz_back_2
	s_cmp_eq_u32 s75, 3
	s_cbranch_scc1 .Lpz_back_3
	s_cmp_eq_u32 s75, 4
	s_cbranch_scc1 .Lpz_back_4
.Lpz_done:
	s_branch .Lpz_resume
.Lpz_resume:
	s_cmp_lt_i32 s41, 2
	s_waitcnt lgkmcnt(0)
	s_barrier
	s_cbranch_scc1 .LBB0_120
	s_waitcnt vmcnt(0)
	s_barrier
	s_mov_b64 s[2:3], exec
	v_readlane_b32 s4, v240, 23
	v_readlane_b32 s5, v240, 24
	s_and_b64 s[4:5], s[2:3], s[4:5]
	s_mov_b64 exec, s[4:5]
	s_cbranch_execz .LBB0_119
	s_add_i32 s4, 0, 0x20160
	v_mov_b32_e32 v2, s4
	s_waitcnt vmcnt(0) expcnt(0) lgkmcnt(0)
	ds_read_b32 v4, v2
	s_add_i32 s4, 0, 0x20164
	v_mov_b32_e32 v2, s4
	ds_read_b32 v2, v2
	s_waitcnt lgkmcnt(1)
	v_cmp_ne_u32_e32 vcc, 0, v4
	s_cbranch_vccnz .LBB0_83
	v_readlane_b32 s4, v240, 2
	v_readlane_b32 s5, v240, 3
	s_load_dwordx2 s[8:9], s[4:5], 0x4
	v_readlane_b32 s10, v240, 20
	v_readlane_b32 s11, v240, 21
	s_add_u32 s4, s10, 0x1000
	s_addc_u32 s5, s11, 0
	s_add_u32 s6, s10, 0x1100
	s_addc_u32 s7, s11, 0
	s_waitcnt lgkmcnt(0)
	s_mul_i32 s18, s8, s92
	s_add_u32 s8, s10, 0x1200
	s_mul_i32 s18, s18, s9
	s_addc_u32 s9, s11, 0
	s_add_u32 s10, s10, 0x1300
	s_addc_u32 s11, s11, 0
	s_mov_b32 s19, 1
	v_mov_b32_e32 v18, 0
	s_branch .LBB0_71

; #define TR_JOB_GU(W_, WT_, off_, gain_) { constexpr int nnb_ = DFF / 32, nit_ = (DM / 64) * nnb_; \
;     if (r < nit_) { const int kb_ = r / nnb_, nb_ = r % nnb_, c0_ = 32 * nb_; \
;         return TrDesc{(W_) + (size_t)(64 * kb_) * DFF + c0_, (WT_) + (size_t)(256 * (c0_ / 128) + (c0_ % 128) + (off_)) * DM + 64 * kb_, (gain_) + 64 * kb_, DFF, DM}; } r -= nit_; }
; __device__ __forceinline__ TrDesc p0_item(const Params& p, int it) {
;     ...
;     TR_JOB_GU(p.ffn_w_gate, WGU0, 0, p.norm_ffn)
;     TR_JOB_GU(p.ffn_w_up, WGU0, 128, p.norm_ffn)
;     TR_JOB(p.ffn_w_down, DM, DFF, 0, DM, WDN0, 0, (const float*)nullptr)
;     TR_JOB(p.cd_w_in, CD_IN, DM, 0, CD_IN, WCD_IN, 0, p.norm_mix + DM)
;     TR_JOB_GU(p.ffn_w_gate + (size_t)DM * DFF, WGU1, 0, p.norm_ffn + DM)
;     TR_JOB_GU(p.ffn_w_up + (size_t)DM * DFF, WGU1, 128, p.norm_ffn + DM)
.Lcv_job_g0:
	s_load_dwordx2 s[60:61], s[24:25], 0x18
	s_load_dwordx2 s[62:63], s[24:25], 0xb8
	s_load_dwordx2 s[4:5], s[24:25], 0x10
	s_mov_b32 s6, 0xac00
	s_mov_b32 s7, 0x2000
	s_mov_b32 s75, 0
	s_and_b32 s9, s18, 63
	s_lshr_b32 s10, s18, 6
	s_add_i32 s10, s10, 0
	s_and_b32 s10, s10, 7
	s_sub_i32 s74, 85, s10
	s_lshr_b32 s74, s74, 3
	s_add_i32 s74, s74, 1
	s_lshl_b32 s11, s9, 6
	s_mul_i32 s11, s11, s6
	s_lshl_b32 s21, s10, 9
	s_add_u32 s11, s11, s21
	s_mul_i32 s23, s10, 256
	s_mul_i32 s23, s23, s7
	s_lshl_b32 s26, s9, 7
	s_add_u32 s23, s23, s26
	s_mov_b32 s70, 0x1000
	s_mov_b32 s71, 0
	s_mov_b32 s72, 0x1000000
	s_mov_b32 s73, 0
	s_waitcnt lgkmcnt(0)
	s_add_u32 s60, s60, s11
	s_addc_u32 s61, s61, 0
	s_add_u32 s62, s62, 0x8100000
	s_addc_u32 s63, s63, 0
	s_add_u32 s62, s62, s23
	s_addc_u32 s63, s63, 0
	s_lshl_b32 s26, s7, 5
	s_add_u32 s64, s62, s26
	s_addc_u32 s65, s63, 0
	s_add_u32 s66, s64, s26
	s_addc_u32 s67, s65, 0
	s_add_u32 s68, s66, s26
	s_addc_u32 s69, s67, 0
	s_lshl_b32 s26, s9, 8
	s_add_u32 s4, s4, s26
	s_addc_u32 s5, s5, 0
	s_mov_b32 s8, 1
	s_branch .Lcv_run
.Lcv_back_0:
.Lcv_job_u0:
	s_load_dwordx2 s[60:61], s[24:25], 0x20
	s_load_dwordx2 s[62:63], s[24:25], 0xb8
	s_load_dwordx2 s[4:5], s[24:25], 0x10
	s_mov_b32 s6, 0xac00
	s_mov_b32 s7, 0x2000
	s_mov_b32 s75, 1
	s_and_b32 s9, s18, 63
	s_lshr_b32 s10, s18, 6
	s_add_i32 s10, s10, 2
	s_and_b32 s10, s10, 7
	s_sub_i32 s74, 85, s10
	s_lshr_b32 s74, s74, 3
	s_add_i32 s74, s74, 1
	s_lshl_b32 s11, s9, 6
	s_mul_i32 s11, s11, s6
	s_lshl_b32 s21, s10, 9
	s_add_u32 s11, s11, s21
	s_mul_i32 s23, s10, 256
	s_add_i32 s23, s23, 128
	s_mul_i32 s23, s23, s7
	s_lshl_b32 s26, s9, 7
	s_add_u32 s23, s23, s26
	s_mov_b32 s70, 0x1000
	s_mov_b32 s71, 0
	s_mov_b32 s72, 0x1000000
	s_mov_b32 s73, 0
	s_waitcnt lgkmcnt(0)
	s_add_u32 s60, s60, s11
	s_addc_u32 s61, s61, 0
	s_add_u32 s62, s62, 0x8100000
	s_addc_u32 s63, s63, 0
	s_add_u32 s62, s62, s23
	s_addc_u32 s63, s63, 0
	s_lshl_b32 s26, s7, 5
	s_add_u32 s64, s62, s26
	s_addc_u32 s65, s63, 0
	s_add_u32 s66, s64, s26
	s_addc_u32 s67, s65, 0
	s_add_u32 s68, s66, s26
	s_addc_u32 s69, s67, 0
	s_lshl_b32 s26, s9, 8
	s_add_u32 s4, s4, s26
	s_addc_u32 s5, s5, 0
	s_mov_b32 s8, 1
	s_branch .Lcv_run
.Lcv_back_1:
.Lcv_job_dn0:
	s_load_dwordx2 s[60:61], s[24:25], 0x28
	s_load_dwordx2 s[62:63], s[24:25], 0xb8
	s_mov_b32 s6, 0x4000
	s_mov_b32 s7, 0x5600
	s_mov_b32 s75, 2
	s_and_b32 s10, s18, 31
	s_lshr_b32 s9, s18, 5
	s_add_i32 s9, s9, 0
	s_and_b32 s9, s9, 15
	s_sub_i32 s74, 171, s9
	s_lshr_b32 s74, s74, 4
	s_add_i32 s74, s74, 1
	s_lshl_b32 s11, s9, 6
	s_mul_i32 s11, s11, s6
	s_lshl_b32 s21, s10, 9
	s_add_u32 s11, s11, s21
	s_lshl_b32 s23, s10, 7
	s_mul_i32 s23, s23, s7
	s_lshl_b32 s26, s9, 7
	s_add_u32 s23, s23, s26
	s_mov_b32 s70, 0x1000000
	s_mov_b32 s71, 0
	s_mov_b32 s72, 0x800
	s_mov_b32 s73, 0
	s_waitcnt lgkmcnt(0)
	s_add_u32 s60, s60, s11
	s_addc_u32 s61, s61, 0
	s_add_u32 s62, s62, 0x12d00000
	s_addc_u32 s63, s63, 0
	s_add_u32 s62, s62, s23
	s_addc_u32 s63, s63, 0
	s_lshl_b32 s26, s7, 5
	s_add_u32 s64, s62, s26
	s_addc_u32 s65, s63, 0
	s_add_u32 s66, s64, s26
	s_addc_u32 s67, s65, 0
	s_add_u32 s68, s66, s26
	s_addc_u32 s69, s67, 0
	s_mov_b32 s8, 0
	s_branch .Lcv_run
.Lcv_back_2:
.Lcv_job_g1:
	s_load_dwordx2 s[60:61], s[24:25], 0x18
	s_load_dwordx2 s[62:63], s[24:25], 0xb8
	s_load_dwordx2 s[4:5], s[24:25], 0x10
	s_mov_b32 s6, 0xac00
	s_mov_b32 s7, 0x2000
	s_mov_b32 s75, 3
	s_and_b32 s9, s18, 63
	s_lshr_b32 s10, s18, 6
	s_add_i32 s10, s10, 4
	s_and_b32 s10, s10, 7
	s_sub_i32 s74, 85, s10
	s_lshr_b32 s74, s74, 3
	s_add_i32 s74, s74, 1
	s_lshl_b32 s11, s9, 6
	s_mul_i32 s11, s11, s6
	s_lshl_b32 s21, s10, 9
	s_add_u32 s11, s11, s21
	s_mul_i32 s23, s10, 256
	s_mul_i32 s23, s23, s7
	s_lshl_b32 s26, s9, 7
	s_add_u32 s23, s23, s26
	s_mov_b32 s70, 0x1000
	s_mov_b32 s71, 0
	s_mov_b32 s72, 0x1000000
	s_mov_b32 s73, 0
	s_waitcnt lgkmcnt(0)
	s_add_u32 s60, s60, 0xac00000
	s_addc_u32 s61, s61, 0
	s_add_u32 s60, s60, s11
	s_addc_u32 s61, s61, 0
	s_add_u32 s62, s62, 0x1f300000
	s_addc_u32 s63, s63, 0
	s_add_u32 s62, s62, s23
	s_addc_u32 s63, s63, 0
	s_lshl_b32 s26, s7, 5
	s_add_u32 s64, s62, s26
	s_addc_u32 s65, s63, 0
	s_add_u32 s66, s64, s26
	s_addc_u32 s67, s65, 0
	s_add_u32 s68, s66, s26
	s_addc_u32 s69, s67, 0
	s_add_u32 s4, s4, 0x4000
	s_addc_u32 s5, s5, 0
	s_lshl_b32 s26, s9, 8
	s_add_u32 s4, s4, s26
	s_addc_u32 s5, s5, 0
	s_mov_b32 s8, 1
	s_branch .Lcv_run
.Lcv_back_3:
.Lcv_job_u1:
	s_load_dwordx2 s[60:61], s[24:25], 0x20
	s_load_dwordx2 s[62:63], s[24:25], 0xb8
	s_load_dwordx2 s[4:5], s[24:25], 0x10
	s_mov_b32 s6, 0xac00
	s_mov_b32 s7, 0x2000
	s_mov_b32 s75, 4
	s_and_b32 s9, s18, 63
	s_lshr_b32 s10, s18, 6
	s_add_i32 s10, s10, 6
	s_and_b32 s10, s10, 7
	s_sub_i32 s74, 85, s10
	s_lshr_b32 s74, s74, 3
	s_add_i32 s74, s74, 1
	s_lshl_b32 s11, s9, 6
	s_mul_i32 s11, s11, s6
	s_lshl_b32 s21, s10, 9
	s_add_u32 s11, s11, s21
	s_mul_i32 s23, s10, 256
	s_add_i32 s23, s23, 128
	s_mul_i32 s23, s23, s7
	s_lshl_b32 s26, s9, 7
	s_add_u32 s23, s23, s26
	s_mov_b32 s70, 0x1000
	s_mov_b32 s71, 0
	s_mov_b32 s72, 0x1000000
	s_mov_b32 s73, 0
	s_waitcnt lgkmcnt(0)
	s_add_u32 s60, s60, 0xac00000
	s_addc_u32 s61, s61, 0
	s_add_u32 s60, s60, s11
	s_addc_u32 s61, s61, 0
	s_add_u32 s62, s62, 0x1f300000
	s_addc_u32 s63, s63, 0
	s_add_u32 s62, s62, s23
	s_addc_u32 s63, s63, 0
	s_lshl_b32 s26, s7, 5
	s_add_u32 s64, s62, s26
	s_addc_u32 s65, s63, 0
	s_add_u32 s66, s64, s26
	s_addc_u32 s67, s65, 0
	s_add_u32 s68, s66, s26
	s_addc_u32 s69, s67, 0
	s_add_u32 s4, s4, 0x4000
	s_addc_u32 s5, s5, 0
	s_lshl_b32 s26, s9, 8
	s_add_u32 s4, s4, s26
	s_addc_u32 s5, s5, 0
	s_mov_b32 s8, 1
	s_branch .Lcv_run

; #define LAS __attribute__((address_space(3)))
; template <class F, bool NT = true> __device__ __forceinline__ void tr_run(F item, int first, int step, int n, LAS float* scr, int lane) {
;     if (first >= n) return;
;     TrDesc da = item(first), db = da, dc = da; f32x4 va[8], vb[8], vc[8];
;     tr_load<NT>(da, va, lane);
;     if (first + step < n) { db = item(first + step); tr_load<NT>(db, vb, lane); }
;     for (int it = first; it < n; it += 3 * step) {
; __device__ __forceinline__ void p0b_convert(const Params& p, LAS unsigned char* lds, int tw, int ntw, int wave, int lane) {
;     P0Item pi{&p, P0A_ITEMS}; tr_run(pi, tw, ntw, P0_NITEMS - P0A_ITEMS, (LAS float*)(lds + wave * 8704), lane);
; }
.Lcv_ret:
	s_cmp_eq_u32 s75, 0
	s_cbranch_scc1 .Lcv_back_0
	s_cmp_eq_u32 s75, 1
	s_cbranch_scc1 .Lcv_back_1
	s_cmp_eq_u32 s75, 2
	s_cbranch_scc1 .Lcv_back_2
	s_cmp_eq_u32 s75, 3
	s_cbranch_scc1 .Lcv_back_3
	s_cmp_eq_u32 s75, 4
	s_cbranch_scc1 .Lcv_back_4
.Lcv_done:
	s_branch .LBB0_663
